# prep weight transposes: all 32 row loads of an item in flight before the LDS writes (two load rounds fused, second register set)
# speedup vs baseline: 1.0262x; 1.0041x over previous
; #define LAS __attribute__((address_space(3)))
; #define LDS_WAIT() asm volatile("s_waitcnt lgkmcnt(0)" ::: "memory")
; __device__ __forceinline__ void transpose_item(const float* W, int K, int N, bf16* WT, bool upmap, LAS float* scr, int item, int lane) {
;     const int nblk = N / 32, kb = item / nblk, nb = item % nblk, k0 = 64 * kb, n0 = 32 * nb;
;     int d0 = n0;
;     if (upmap) { const int f = n0 < DFF ? n0 : n0 - DFF; d0 = (f >> 7) * 256 + (f & 127) + (n0 < DFF ? 0 : 128); }
; #pragma unroll 8
;     for (int i = 0; i < 32; ++i) { const int kk = 2 * i + (lane >> 5); scr[kk * 33 + (lane & 31)] = W[(size_t)(k0 + kk) * N + n0 + (lane & 31)]; }
;     LDS_WAIT(); asm volatile("" ::: "memory");
.LBB0_417:
	s_lshl_b32 s20, s5, 1
	s_lshl_b32 s21, s12, 1
	v_or_b32_e32 v16, s21, v10
	s_add_i32 s26, s20, 4
	s_add_i32 s27, s21, 4
	s_add_i32 s28, s20, 8
	s_add_i32 s29, s21, 8
	s_add_i32 s18, s20, 12
	s_add_i32 s19, s21, 12
	s_add_i32 s31, s20, 16
	s_add_i32 s35, s21, 16
	s_add_i32 s36, s20, 20
	s_add_i32 s37, s21, 20
	s_add_i32 s38, s20, 24
	s_add_i32 s40, s21, 24
	s_add_i32 s41, s20, 28
	s_add_i32 s42, s21, 28
	v_or_b32_e32 v14, s20, v3
	v_ashrrev_i32_e32 v17, 31, v16
	v_or_b32_e32 v18, s26, v3
	v_or_b32_e32 v20, s27, v10
	v_or_b32_e32 v22, s28, v3
	v_or_b32_e32 v24, s29, v10
	v_or_b32_e32 v26, s18, v3
	v_or_b32_e32 v28, s19, v10
	v_or_b32_e32 v30, s31, v3
	v_or_b32_e32 v32, s35, v10
	v_or_b32_e32 v34, s36, v3
	v_or_b32_e32 v36, s37, v10
	v_or_b32_e32 v38, s38, v3
	v_or_b32_e32 v40, s40, v10
	v_or_b32_e32 v42, s41, v3
	v_or_b32_e32 v44, s42, v10
	v_ashrrev_i32_e32 v15, 31, v14
	v_lshlrev_b64 v[16:17], 12, v[16:17]
	v_ashrrev_i32_e32 v21, 31, v20
	v_ashrrev_i32_e32 v19, 31, v18
	v_ashrrev_i32_e32 v25, 31, v24
	v_ashrrev_i32_e32 v23, 31, v22
	v_ashrrev_i32_e32 v29, 31, v28
	v_ashrrev_i32_e32 v27, 31, v26
	v_ashrrev_i32_e32 v33, 31, v32
	v_ashrrev_i32_e32 v31, 31, v30
	v_ashrrev_i32_e32 v37, 31, v36
	v_ashrrev_i32_e32 v35, 31, v34
	v_ashrrev_i32_e32 v41, 31, v40
	v_ashrrev_i32_e32 v39, 31, v38
	v_ashrrev_i32_e32 v45, 31, v44
	v_ashrrev_i32_e32 v43, 31, v42
	v_lshlrev_b64 v[14:15], 12, v[14:15]
	v_lshl_add_u64 v[16:17], v[8:9], 0, v[16:17]
	v_lshlrev_b64 v[18:19], 12, v[18:19]
	v_lshlrev_b64 v[20:21], 12, v[20:21]
	v_lshlrev_b64 v[22:23], 12, v[22:23]
	v_lshlrev_b64 v[24:25], 12, v[24:25]
	v_lshlrev_b64 v[26:27], 12, v[26:27]
	v_lshlrev_b64 v[28:29], 12, v[28:29]
	v_lshlrev_b64 v[30:31], 12, v[30:31]
	v_lshlrev_b64 v[32:33], 12, v[32:33]
	v_lshlrev_b64 v[34:35], 12, v[34:35]
	v_lshlrev_b64 v[36:37], 12, v[36:37]
	v_lshlrev_b64 v[38:39], 12, v[38:39]
	v_lshlrev_b64 v[40:41], 12, v[40:41]
	v_lshlrev_b64 v[42:43], 12, v[42:43]
	v_lshlrev_b64 v[44:45], 12, v[44:45]
	v_lshl_add_u64 v[14:15], v[8:9], 0, v[14:15]
	v_lshl_add_u64 v[20:21], v[8:9], 0, v[20:21]
	v_lshl_add_u64 v[18:19], v[8:9], 0, v[18:19]
	v_lshl_add_u64 v[24:25], v[8:9], 0, v[24:25]
	v_lshl_add_u64 v[22:23], v[8:9], 0, v[22:23]
	v_lshl_add_u64 v[28:29], v[8:9], 0, v[28:29]
	v_lshl_add_u64 v[26:27], v[8:9], 0, v[26:27]
	v_lshl_add_u64 v[32:33], v[8:9], 0, v[32:33]
	v_lshl_add_u64 v[30:31], v[8:9], 0, v[30:31]
	v_lshl_add_u64 v[36:37], v[8:9], 0, v[36:37]
	v_lshl_add_u64 v[34:35], v[8:9], 0, v[34:35]
	v_lshl_add_u64 v[40:41], v[8:9], 0, v[40:41]
	v_lshl_add_u64 v[38:39], v[8:9], 0, v[38:39]
	v_lshl_add_u64 v[44:45], v[8:9], 0, v[44:45]
	v_lshl_add_u64 v[42:43], v[8:9], 0, v[42:43]
	global_load_dword v46, v[16:17], off
	global_load_dword v47, v[14:15], off
	global_load_dword v48, v[20:21], off
	global_load_dword v49, v[18:19], off
	global_load_dword v50, v[24:25], off
	global_load_dword v51, v[22:23], off
	global_load_dword v52, v[28:29], off
	global_load_dword v53, v[26:27], off
	global_load_dword v54, v[32:33], off
	global_load_dword v55, v[30:31], off
	global_load_dword v56, v[36:37], off
	global_load_dword v57, v[34:35], off
	global_load_dword v58, v[40:41], off
	global_load_dword v59, v[38:39], off
	global_load_dword v60, v[44:45], off
	global_load_dword v61, v[42:43], off
	v_or_b32_e32 v64, s20, v1
	v_or_b32_e32 v62, s21, v0
	s_add_i32 s12, s12, 16
	s_add_i32 s5, s5, 16
	s_add_i32 s13, s13, -16
	v_mad_u64_u32 v[62:63], s[20:21], v62, s81, v[4:5]
	v_mad_u64_u32 v[64:65], s[20:21], v64, s81, v[4:5]
	v_or_b32_e32 v63, s26, v1
	v_or_b32_e32 v65, s27, v0
	v_or_b32_e32 v72, s28, v1
	v_or_b32_e32 v70, s29, v0
	v_or_b32_e32 v76, s18, v1
	v_or_b32_e32 v74, s19, v0
	v_or_b32_e32 v80, s31, v1
	v_or_b32_e32 v78, s35, v0
	v_or_b32_e32 v84, s36, v1
	v_or_b32_e32 v82, s37, v0
	v_or_b32_e32 v88, s38, v1
	v_or_b32_e32 v86, s40, v0
	v_or_b32_e32 v92, s41, v1
	v_or_b32_e32 v90, s42, v0
	s_cmp_lg_u32 s13, 0
	v_mad_u64_u32 v[66:67], s[20:21], v65, s81, v[4:5]
	v_mad_u64_u32 v[68:69], s[20:21], v63, s81, v[4:5]
	v_mad_u64_u32 v[70:71], s[20:21], v70, s81, v[4:5]
	v_mad_u64_u32 v[72:73], s[20:21], v72, s81, v[4:5]
	v_mad_u64_u32 v[74:75], s[20:21], v74, s81, v[4:5]
	v_mad_u64_u32 v[76:77], s[20:21], v76, s81, v[4:5]
	v_mad_u64_u32 v[78:79], s[20:21], v78, s81, v[4:5]
	v_mad_u64_u32 v[80:81], s[20:21], v80, s81, v[4:5]
	v_mad_u64_u32 v[82:83], s[20:21], v82, s81, v[4:5]
	v_mad_u64_u32 v[84:85], s[20:21], v84, s81, v[4:5]
	v_mad_u64_u32 v[86:87], s[20:21], v86, s81, v[4:5]
	v_mad_u64_u32 v[88:89], s[20:21], v88, s81, v[4:5]
	v_mad_u64_u32 v[90:91], s[20:21], v90, s81, v[4:5]
	v_mad_u64_u32 v[92:93], s[20:21], v92, s81, v[4:5]
	s_lshl_b32 s20, s5, 1
	s_lshl_b32 s21, s12, 1
	v_or_b32_e32 v16, s21, v10
	s_add_i32 s26, s20, 4
	s_add_i32 s27, s21, 4
	s_add_i32 s28, s20, 8
	s_add_i32 s29, s21, 8
	s_add_i32 s18, s20, 12
	s_add_i32 s19, s21, 12
	s_add_i32 s31, s20, 16
	s_add_i32 s35, s21, 16
	s_add_i32 s36, s20, 20
	s_add_i32 s37, s21, 20
	s_add_i32 s38, s20, 24
	s_add_i32 s40, s21, 24
	s_add_i32 s41, s20, 28
	s_add_i32 s42, s21, 28
	v_or_b32_e32 v14, s20, v3
	v_ashrrev_i32_e32 v17, 31, v16
	v_or_b32_e32 v18, s26, v3
	v_or_b32_e32 v20, s27, v10
	v_or_b32_e32 v22, s28, v3
	v_or_b32_e32 v24, s29, v10
	v_or_b32_e32 v26, s18, v3
	v_or_b32_e32 v28, s19, v10
	v_or_b32_e32 v30, s31, v3
	v_or_b32_e32 v32, s35, v10
	v_or_b32_e32 v34, s36, v3
	v_or_b32_e32 v36, s37, v10
	v_or_b32_e32 v38, s38, v3
	v_or_b32_e32 v40, s40, v10
	v_or_b32_e32 v42, s41, v3
	v_or_b32_e32 v44, s42, v10
	v_ashrrev_i32_e32 v15, 31, v14
	v_lshlrev_b64 v[16:17], 12, v[16:17]
	v_ashrrev_i32_e32 v21, 31, v20
	v_ashrrev_i32_e32 v19, 31, v18
; #define LDS_WAIT() asm volatile("s_waitcnt lgkmcnt(0)" ::: "memory")
; __device__ __forceinline__ void transpose_item(const float* W, int K, int N, bf16* WT, bool upmap, LAS float* scr, int item, int lane) {
;     ...
; #pragma unroll 8
;     for (int i = 0; i < 32; ++i) { const int kk = 2 * i + (lane >> 5); scr[kk * 33 + (lane & 31)] = W[(size_t)(k0 + kk) * N + n0 + (lane & 31)]; }
;     LDS_WAIT(); asm volatile("" ::: "memory");
	v_ashrrev_i32_e32 v25, 31, v24
	v_ashrrev_i32_e32 v23, 31, v22
	v_ashrrev_i32_e32 v29, 31, v28
	v_ashrrev_i32_e32 v27, 31, v26
	v_ashrrev_i32_e32 v33, 31, v32
	v_ashrrev_i32_e32 v31, 31, v30
	v_ashrrev_i32_e32 v37, 31, v36
	v_ashrrev_i32_e32 v35, 31, v34
	v_ashrrev_i32_e32 v41, 31, v40
	v_ashrrev_i32_e32 v39, 31, v38
	v_ashrrev_i32_e32 v45, 31, v44
	v_ashrrev_i32_e32 v43, 31, v42
	v_lshlrev_b64 v[14:15], 12, v[14:15]
	v_lshl_add_u64 v[16:17], v[8:9], 0, v[16:17]
	v_lshlrev_b64 v[18:19], 12, v[18:19]
	v_lshlrev_b64 v[20:21], 12, v[20:21]
	v_lshlrev_b64 v[22:23], 12, v[22:23]
	v_lshlrev_b64 v[24:25], 12, v[24:25]
	v_lshlrev_b64 v[26:27], 12, v[26:27]
	v_lshlrev_b64 v[28:29], 12, v[28:29]
	v_lshlrev_b64 v[30:31], 12, v[30:31]
	v_lshlrev_b64 v[32:33], 12, v[32:33]
	v_lshlrev_b64 v[34:35], 12, v[34:35]
	v_lshlrev_b64 v[36:37], 12, v[36:37]
	v_lshlrev_b64 v[38:39], 12, v[38:39]
	v_lshlrev_b64 v[40:41], 12, v[40:41]
	v_lshlrev_b64 v[42:43], 12, v[42:43]
	v_lshlrev_b64 v[44:45], 12, v[44:45]
	v_lshl_add_u64 v[14:15], v[8:9], 0, v[14:15]
	v_lshl_add_u64 v[20:21], v[8:9], 0, v[20:21]
	v_lshl_add_u64 v[18:19], v[8:9], 0, v[18:19]
	v_lshl_add_u64 v[24:25], v[8:9], 0, v[24:25]
	v_lshl_add_u64 v[22:23], v[8:9], 0, v[22:23]
	v_lshl_add_u64 v[28:29], v[8:9], 0, v[28:29]
	v_lshl_add_u64 v[26:27], v[8:9], 0, v[26:27]
	v_lshl_add_u64 v[32:33], v[8:9], 0, v[32:33]
	v_lshl_add_u64 v[30:31], v[8:9], 0, v[30:31]
	v_lshl_add_u64 v[36:37], v[8:9], 0, v[36:37]
	v_lshl_add_u64 v[34:35], v[8:9], 0, v[34:35]
	v_lshl_add_u64 v[40:41], v[8:9], 0, v[40:41]
	v_lshl_add_u64 v[38:39], v[8:9], 0, v[38:39]
	v_lshl_add_u64 v[44:45], v[8:9], 0, v[44:45]
	v_lshl_add_u64 v[42:43], v[8:9], 0, v[42:43]
	global_load_dword v94, v[16:17], off
	global_load_dword v95, v[14:15], off
	global_load_dword v96, v[20:21], off
	global_load_dword v97, v[18:19], off
	global_load_dword v98, v[24:25], off
	global_load_dword v99, v[22:23], off
	global_load_dword v100, v[28:29], off
	global_load_dword v101, v[26:27], off
	global_load_dword v102, v[32:33], off
	global_load_dword v103, v[30:31], off
	global_load_dword v104, v[36:37], off
	global_load_dword v105, v[34:35], off
	global_load_dword v106, v[40:41], off
	global_load_dword v107, v[38:39], off
	global_load_dword v108, v[44:45], off
	global_load_dword v109, v[42:43], off
	s_waitcnt vmcnt(31)
	ds_write_b32 v62, v46
	s_waitcnt vmcnt(30)
	ds_write_b32 v64, v47
	s_waitcnt vmcnt(29)
	ds_write_b32 v66, v48
	s_waitcnt vmcnt(28)
	ds_write_b32 v68, v49
	s_waitcnt vmcnt(27)
	ds_write_b32 v70, v50
	s_waitcnt vmcnt(26)
	ds_write_b32 v72, v51
	s_waitcnt vmcnt(25)
	ds_write_b32 v74, v52
	s_waitcnt vmcnt(24)
	ds_write_b32 v76, v53
	s_waitcnt vmcnt(23)
	ds_write_b32 v78, v54
	s_waitcnt vmcnt(22)
	ds_write_b32 v80, v55
	s_waitcnt vmcnt(21)
	ds_write_b32 v82, v56
	s_waitcnt vmcnt(20)
	ds_write_b32 v84, v57
	s_waitcnt vmcnt(19)
	ds_write_b32 v86, v58
	s_waitcnt vmcnt(18)
	ds_write_b32 v88, v59
	s_waitcnt vmcnt(17)
	ds_write_b32 v90, v60
	s_waitcnt vmcnt(16)
	ds_write_b32 v92, v61
	v_or_b32_e32 v16, s20, v1
	v_or_b32_e32 v14, s21, v0
	s_add_i32 s12, s12, 16
	s_add_i32 s5, s5, 16
	s_add_i32 s13, s13, -16
	v_mad_u64_u32 v[14:15], s[20:21], v14, s81, v[4:5]
	v_mad_u64_u32 v[16:17], s[20:21], v16, s81, v[4:5]
	v_or_b32_e32 v15, s26, v1
	v_or_b32_e32 v17, s27, v0
	v_or_b32_e32 v24, s28, v1
	v_or_b32_e32 v22, s29, v0
	v_or_b32_e32 v28, s18, v1
	v_or_b32_e32 v26, s19, v0
	v_or_b32_e32 v32, s31, v1
	v_or_b32_e32 v30, s35, v0
	v_or_b32_e32 v36, s36, v1
	v_or_b32_e32 v34, s37, v0
	v_or_b32_e32 v40, s38, v1
	v_or_b32_e32 v38, s40, v0
	v_or_b32_e32 v44, s41, v1
	v_or_b32_e32 v42, s42, v0
	s_cmp_lg_u32 s13, 0
	v_mad_u64_u32 v[18:19], s[20:21], v17, s81, v[4:5]
	v_mad_u64_u32 v[20:21], s[20:21], v15, s81, v[4:5]
	v_mad_u64_u32 v[22:23], s[20:21], v22, s81, v[4:5]
	v_mad_u64_u32 v[24:25], s[20:21], v24, s81, v[4:5]
	v_mad_u64_u32 v[26:27], s[20:21], v26, s81, v[4:5]
	v_mad_u64_u32 v[28:29], s[20:21], v28, s81, v[4:5]
	v_mad_u64_u32 v[30:31], s[20:21], v30, s81, v[4:5]
	v_mad_u64_u32 v[32:33], s[20:21], v32, s81, v[4:5]
	v_mad_u64_u32 v[34:35], s[20:21], v34, s81, v[4:5]
	v_mad_u64_u32 v[36:37], s[20:21], v36, s81, v[4:5]
	v_mad_u64_u32 v[38:39], s[20:21], v38, s81, v[4:5]
	v_mad_u64_u32 v[40:41], s[20:21], v40, s81, v[4:5]
	v_mad_u64_u32 v[42:43], s[20:21], v42, s81, v[4:5]
	v_mad_u64_u32 v[44:45], s[20:21], v44, s81, v[4:5]
	s_waitcnt vmcnt(15)
	ds_write_b32 v14, v94
	s_waitcnt vmcnt(14)
	ds_write_b32 v16, v95
	s_waitcnt vmcnt(13)
	ds_write_b32 v18, v96
	s_waitcnt vmcnt(12)
	ds_write_b32 v20, v97
	s_waitcnt vmcnt(11)
	ds_write_b32 v22, v98
	s_waitcnt vmcnt(10)
	ds_write_b32 v24, v99
	s_waitcnt vmcnt(9)
	ds_write_b32 v26, v100
	s_waitcnt vmcnt(8)
	ds_write_b32 v28, v101
	s_waitcnt vmcnt(7)
	ds_write_b32 v30, v102
	s_waitcnt vmcnt(6)
	ds_write_b32 v32, v103
	s_waitcnt vmcnt(5)
	ds_write_b32 v34, v104
	s_waitcnt vmcnt(4)
	ds_write_b32 v36, v105
	s_waitcnt vmcnt(3)
	ds_write_b32 v38, v106
	s_waitcnt vmcnt(2)
	ds_write_b32 v40, v107
	s_waitcnt vmcnt(1)
	ds_write_b32 v42, v108
	s_waitcnt vmcnt(0)
; #define GAS __attribute__((address_space(1)))
; #define LAS __attribute__((address_space(3)))
; #define LDS_WAIT() asm volatile("s_waitcnt lgkmcnt(0)" ::: "memory")
; __device__ __forceinline__ unsigned pk2(float lo, float hi) { return f2bf(lo) | (f2bf(hi) << 16); }
; __device__ __forceinline__ void transpose_item(const float* W, int K, int N, bf16* WT, bool upmap, LAS float* scr, int item, int lane) {
;     ...
;     for (int i = 0; i < 32; ++i) { const int kk = 2 * i + (lane >> 5); scr[kk * 33 + (lane & 31)] = W[(size_t)(k0 + kk) * N + n0 + (lane & 31)]; }
;     LDS_WAIT(); asm volatile("" ::: "memory");
;     const int c = lane & 7;
; #pragma unroll
;     for (int j = 0; j < 4; ++j) { const int n = (lane >> 3) + 8 * j; const LAS float* s = scr + (8 * c) * 33 + n;
;         v4u o; o.x = pk2(s[0 * 33], s[1 * 33]); o.y = pk2(s[2 * 33], s[3 * 33]); o.z = pk2(s[4 * 33], s[5 * 33]); o.w = pk2(s[6 * 33], s[7 * 33]);
;         *(GAS v4u*)(WT + (size_t)(d0 + n) * K + k0 + 8 * c) = o; }
;     LDS_WAIT(); asm volatile("" ::: "memory");
	ds_write_b32 v44, v109
	s_waitcnt lgkmcnt(0)
	ds_read2_b32 v[8:9], v7 offset1:8
	ds_read2_b32 v[20:21], v7 offset0:33 offset1:41
	ds_read2_b32 v[22:23], v7 offset0:66 offset1:74
	s_lshl_b64 s[12:13], s[16:17], 1
	ds_read2_b32 v[24:25], v7 offset0:99 offset1:107
	s_add_u32 s12, s10, s12
	s_waitcnt lgkmcnt(3)
	v_bfe_u32 v3, v8, 16, 1
	s_addc_u32 s13, s9, s13
	v_lshlrev_b32_e32 v208, 1, v6
	v_add3_u32 v3, v8, v3, s33
	s_waitcnt lgkmcnt(2)
	v_bfe_u32 v8, v20, 16, 1
	ds_read2_b32 v[26:27], v7 offset0:132 offset1:140
	v_lshl_add_u64 v[14:15], s[12:13], 0, v[208:209]
	s_mov_b64 s[12:13], 0x1f00000
	v_lshrrev_b32_e32 v3, 16, v3
	v_add3_u32 v8, v20, v8, s33
	ds_read2_b32 v[28:29], v7 offset0:165 offset1:173
	v_lshl_add_u64 v[18:19], v[14:15], 0, s[12:13]
	v_and_or_b32 v14, v8, s80, v3
	s_waitcnt lgkmcnt(3)
	v_bfe_u32 v3, v22, 16, 1
	v_add3_u32 v3, v22, v3, s33
	s_waitcnt lgkmcnt(2)
	v_bfe_u32 v8, v24, 16, 1
	ds_read2_b32 v[30:31], v7 offset0:198 offset1:206
	v_lshrrev_b32_e32 v3, 16, v3
	v_add3_u32 v8, v24, v8, s33
	ds_read2_b32 v[32:33], v7 offset0:231 offset1:239
	v_and_or_b32 v15, v8, s80, v3
	s_waitcnt lgkmcnt(3)
	v_bfe_u32 v3, v26, 16, 1
	v_add3_u32 v3, v26, v3, s33
	s_waitcnt lgkmcnt(2)
	v_bfe_u32 v8, v28, 16, 1
	v_lshrrev_b32_e32 v3, 16, v3
	v_add3_u32 v8, v28, v8, s33
	v_and_or_b32 v16, v8, s80, v3
	s_waitcnt lgkmcnt(1)
	v_bfe_u32 v3, v30, 16, 1
	v_add3_u32 v3, v30, v3, s33
	s_waitcnt lgkmcnt(0)
	v_bfe_u32 v8, v32, 16, 1
	v_lshrrev_b32_e32 v3, 16, v3
	v_add3_u32 v8, v32, v8, s33
	v_and_or_b32 v17, v8, s80, v3
	v_or_b32_e32 v3, s4, v5
	v_mul_u32_u24_e32 v3, 0xb00, v3
	v_lshlrev_b32_e32 v208, 1, v3
	v_bfe_u32 v3, v9, 16, 1
	v_add3_u32 v3, v9, v3, s33
	v_bfe_u32 v8, v21, 16, 1
	v_lshl_add_u64 v[34:35], v[18:19], 0, v[208:209]
	v_lshrrev_b32_e32 v3, 16, v3
	v_add3_u32 v8, v21, v8, s33
	global_store_dwordx4 v[34:35], v[14:17], off
	v_readlane_b32 s42, v254, 31
	v_readlane_b32 s43, v254, 32
	v_and_or_b32 v14, v8, s80, v3
	v_bfe_u32 v3, v23, 16, 1
	v_add3_u32 v3, v23, v3, s33
	v_bfe_u32 v8, v25, 16, 1
	v_lshrrev_b32_e32 v3, 16, v3
	v_add3_u32 v8, v25, v8, s33
	v_and_or_b32 v15, v8, s80, v3
	v_bfe_u32 v3, v27, 16, 1
	v_add3_u32 v3, v27, v3, s33
	v_bfe_u32 v8, v29, 16, 1
	v_lshrrev_b32_e32 v3, 16, v3
	v_add3_u32 v8, v29, v8, s33
	v_and_or_b32 v16, v8, s80, v3
	v_bfe_u32 v3, v31, 16, 1
	v_add3_u32 v3, v31, v3, s33
	v_bfe_u32 v8, v33, 16, 1
	v_lshrrev_b32_e32 v3, 16, v3
	v_add3_u32 v8, v33, v8, s33
	v_and_or_b32 v17, v8, s80, v3
	v_or_b32_e32 v3, s4, v11
	v_mul_u32_u24_e32 v3, 0xb00, v3
	v_lshlrev_b32_e32 v208, 1, v3
	ds_read2_b32 v[8:9], v7 offset0:16 offset1:24
	v_lshl_add_u64 v[20:21], v[18:19], 0, v[208:209]
	global_store_dwordx4 v[20:21], v[14:17], off
	ds_read2_b32 v[20:21], v7 offset0:49 offset1:57
	ds_read2_b32 v[22:23], v7 offset0:82 offset1:90
	ds_read2_b32 v[24:25], v7 offset0:115 offset1:123
	s_waitcnt lgkmcnt(3)
	v_bfe_u32 v3, v8, 16, 1
	v_add3_u32 v3, v8, v3, s33
	s_waitcnt lgkmcnt(2)
	v_bfe_u32 v8, v20, 16, 1
	ds_read2_b32 v[26:27], v7 offset0:148 offset1:156
	v_lshrrev_b32_e32 v3, 16, v3
	v_add3_u32 v8, v20, v8, s33
	ds_read2_b32 v[28:29], v7 offset0:181 offset1:189
	v_and_or_b32 v14, v8, s80, v3
	s_waitcnt lgkmcnt(3)
	v_bfe_u32 v3, v22, 16, 1
	v_add3_u32 v3, v22, v3, s33
	s_waitcnt lgkmcnt(2)
	v_bfe_u32 v8, v24, 16, 1
	ds_read2_b32 v[30:31], v7 offset0:214 offset1:222
	v_lshrrev_b32_e32 v3, 16, v3
	v_add3_u32 v8, v24, v8, s33
	ds_read2_b32 v[32:33], v7 offset0:247 offset1:255
	v_and_or_b32 v15, v8, s80, v3
	s_waitcnt lgkmcnt(3)
	v_bfe_u32 v3, v26, 16, 1
	v_add3_u32 v3, v26, v3, s33
	s_waitcnt lgkmcnt(2)
	v_bfe_u32 v8, v28, 16, 1
	v_lshrrev_b32_e32 v3, 16, v3
	v_add3_u32 v8, v28, v8, s33
	v_and_or_b32 v16, v8, s80, v3
	s_waitcnt lgkmcnt(1)
	v_bfe_u32 v3, v30, 16, 1
	v_add3_u32 v3, v30, v3, s33
	s_waitcnt lgkmcnt(0)
	v_bfe_u32 v8, v32, 16, 1
	v_lshrrev_b32_e32 v3, 16, v3
	v_add3_u32 v8, v32, v8, s33
	v_and_or_b32 v17, v8, s80, v3
	v_or_b32_e32 v3, s4, v12
	v_mul_u32_u24_e32 v3, 0xb00, v3
	v_lshlrev_b32_e32 v208, 1, v3
	v_bfe_u32 v3, v9, 16, 1
	v_add3_u32 v3, v9, v3, s33
	v_bfe_u32 v8, v21, 16, 1
	v_lshl_add_u64 v[34:35], v[18:19], 0, v[208:209]
	v_lshrrev_b32_e32 v3, 16, v3
	v_add3_u32 v8, v21, v8, s33
	global_store_dwordx4 v[34:35], v[14:17], off
	s_nop 1
	v_and_or_b32 v14, v8, s80, v3
	v_bfe_u32 v3, v23, 16, 1
	v_add3_u32 v3, v23, v3, s33
	v_bfe_u32 v8, v25, 16, 1
	v_lshrrev_b32_e32 v3, 16, v3
	v_add3_u32 v8, v25, v8, s33
	v_and_or_b32 v15, v8, s80, v3
	v_bfe_u32 v3, v27, 16, 1
	v_add3_u32 v3, v27, v3, s33
	v_bfe_u32 v8, v29, 16, 1
	v_lshrrev_b32_e32 v3, 16, v3
	v_add3_u32 v8, v29, v8, s33
	v_and_or_b32 v16, v8, s80, v3
	v_bfe_u32 v3, v31, 16, 1
	v_add3_u32 v3, v31, v3, s33
	v_bfe_u32 v8, v33, 16, 1
	v_lshrrev_b32_e32 v3, 16, v3
	v_add3_u32 v8, v33, v8, s33
	v_and_or_b32 v17, v8, s80, v3
	v_or_b32_e32 v3, s4, v13
	v_mul_u32_u24_e32 v3, 0xb00, v3
	v_lshlrev_b32_e32 v208, 1, v3
	v_lshl_add_u64 v[8:9], v[18:19], 0, v[208:209]
	global_store_dwordx4 v[8:9], v[14:17], off
	s_waitcnt lgkmcnt(0)
	s_mov_b64 s[4:5], 0

; #define LAS __attribute__((address_space(3)))
; #define LDS_WAIT() asm volatile("s_waitcnt lgkmcnt(0)" ::: "memory")
; __device__ __forceinline__ void transpose_item(const float* W, int K, int N, bf16* WT, bool upmap, LAS float* scr, int item, int lane) {
;     const int nblk = N / 32, kb = item / nblk, nb = item % nblk, k0 = 64 * kb, n0 = 32 * nb;
;     int d0 = n0;
;     if (upmap) { const int f = n0 < DFF ? n0 : n0 - DFF; d0 = (f >> 7) * 256 + (f & 127) + (n0 < DFF ? 0 : 128); }
; #pragma unroll 8
;     for (int i = 0; i < 32; ++i) { const int kk = 2 * i + (lane >> 5); scr[kk * 33 + (lane & 31)] = W[(size_t)(k0 + kk) * N + n0 + (lane & 31)]; }
;     LDS_WAIT(); asm volatile("" ::: "memory");
.LBB0_421:
	s_lshl_b32 s18, s13, 1
	s_lshl_b32 s19, s16, 1
	v_or_b32_e32 v14, s19, v10
	s_add_i32 s21, s18, 4
	s_add_i32 s28, s19, 4
	s_add_i32 s29, s18, 8
	s_add_i32 s31, s19, 8
	s_add_i32 s35, s18, 12
	s_add_i32 s36, s19, 12
	s_add_i32 s37, s18, 16
	s_add_i32 s38, s19, 16
	s_add_i32 s40, s18, 20
	s_add_i32 s41, s19, 20
	s_add_i32 s42, s18, 24
	s_add_i32 s43, s19, 24
	s_add_i32 s44, s18, 28
	s_add_i32 s45, s19, 28
	v_or_b32_e32 v16, s18, v3
	v_mad_u64_u32 v[14:15], s[26:27], v14, s87, v[8:9]
	v_or_b32_e32 v20, s21, v3
	v_or_b32_e32 v18, s28, v10
	v_or_b32_e32 v24, s29, v3
	v_or_b32_e32 v22, s31, v10
	v_or_b32_e32 v28, s35, v3
	v_or_b32_e32 v26, s36, v10
	v_or_b32_e32 v32, s37, v3
	v_or_b32_e32 v30, s38, v10
	v_or_b32_e32 v36, s40, v3
	v_or_b32_e32 v34, s41, v10
	v_or_b32_e32 v40, s42, v3
	v_or_b32_e32 v38, s43, v10
	v_or_b32_e32 v44, s44, v3
	v_or_b32_e32 v42, s45, v10
	v_mad_u64_u32 v[16:17], s[26:27], v16, s87, v[8:9]
	v_mad_u64_u32 v[18:19], s[26:27], v18, s87, v[8:9]
	v_mad_u64_u32 v[20:21], s[26:27], v20, s87, v[8:9]
	v_mad_u64_u32 v[22:23], s[26:27], v22, s87, v[8:9]
	v_mad_u64_u32 v[24:25], s[26:27], v24, s87, v[8:9]
	v_mad_u64_u32 v[26:27], s[26:27], v26, s87, v[8:9]
	v_mad_u64_u32 v[28:29], s[26:27], v28, s87, v[8:9]
	v_mad_u64_u32 v[30:31], s[26:27], v30, s87, v[8:9]
	v_mad_u64_u32 v[32:33], s[26:27], v32, s87, v[8:9]
	v_mad_u64_u32 v[34:35], s[26:27], v34, s87, v[8:9]
	v_mad_u64_u32 v[36:37], s[26:27], v36, s87, v[8:9]
	v_mad_u64_u32 v[38:39], s[26:27], v38, s87, v[8:9]
	v_mad_u64_u32 v[40:41], s[26:27], v40, s87, v[8:9]
	v_mad_u64_u32 v[42:43], s[26:27], v42, s87, v[8:9]
	v_mad_u64_u32 v[44:45], s[26:27], v44, s87, v[8:9]
	global_load_dword v46, v[14:15], off
	global_load_dword v47, v[16:17], off
	global_load_dword v48, v[18:19], off
	global_load_dword v49, v[20:21], off
	global_load_dword v50, v[22:23], off
	global_load_dword v51, v[24:25], off
	global_load_dword v52, v[26:27], off
	global_load_dword v53, v[28:29], off
	global_load_dword v54, v[30:31], off
	global_load_dword v55, v[32:33], off
	global_load_dword v56, v[34:35], off
	global_load_dword v57, v[36:37], off
	global_load_dword v58, v[38:39], off
	global_load_dword v59, v[40:41], off
	global_load_dword v60, v[42:43], off
	global_load_dword v61, v[44:45], off
	v_or_b32_e32 v64, s18, v1
	v_or_b32_e32 v62, s19, v0
	s_add_i32 s16, s16, 16
	s_add_i32 s13, s13, 16
	s_add_i32 s20, s20, -16
	v_mad_u64_u32 v[62:63], s[26:27], v62, s81, v[4:5]
	v_mad_u64_u32 v[64:65], s[26:27], v64, s81, v[4:5]
	v_or_b32_e32 v63, s21, v1
	v_or_b32_e32 v65, s28, v0
	v_or_b32_e32 v72, s29, v1
	v_or_b32_e32 v70, s31, v0
	v_or_b32_e32 v76, s35, v1
	v_or_b32_e32 v74, s36, v0
	v_or_b32_e32 v80, s37, v1
	v_or_b32_e32 v78, s38, v0
	v_or_b32_e32 v84, s40, v1
	v_or_b32_e32 v82, s41, v0
	v_or_b32_e32 v88, s42, v1
	v_or_b32_e32 v86, s43, v0
	v_or_b32_e32 v92, s44, v1
	v_or_b32_e32 v90, s45, v0
	s_cmp_lg_u32 s20, 0
	v_mad_u64_u32 v[66:67], s[26:27], v65, s81, v[4:5]
	v_mad_u64_u32 v[68:69], s[26:27], v63, s81, v[4:5]
	v_mad_u64_u32 v[70:71], s[26:27], v70, s81, v[4:5]
	v_mad_u64_u32 v[72:73], s[26:27], v72, s81, v[4:5]
	v_mad_u64_u32 v[74:75], s[26:27], v74, s81, v[4:5]
	v_mad_u64_u32 v[76:77], s[26:27], v76, s81, v[4:5]
	v_mad_u64_u32 v[78:79], s[26:27], v78, s81, v[4:5]
	v_mad_u64_u32 v[80:81], s[26:27], v80, s81, v[4:5]
	v_mad_u64_u32 v[82:83], s[26:27], v82, s81, v[4:5]
	v_mad_u64_u32 v[84:85], s[26:27], v84, s81, v[4:5]
	v_mad_u64_u32 v[86:87], s[26:27], v86, s81, v[4:5]
	v_mad_u64_u32 v[88:89], s[26:27], v88, s81, v[4:5]
	v_mad_u64_u32 v[90:91], s[26:27], v90, s81, v[4:5]
	v_mad_u64_u32 v[92:93], s[26:27], v92, s81, v[4:5]
	s_lshl_b32 s18, s13, 1
	s_lshl_b32 s19, s16, 1
	v_or_b32_e32 v14, s19, v10
	s_add_i32 s21, s18, 4
	s_add_i32 s28, s19, 4
	s_add_i32 s29, s18, 8
	s_add_i32 s31, s19, 8
	s_add_i32 s35, s18, 12
	s_add_i32 s36, s19, 12
	s_add_i32 s37, s18, 16
	s_add_i32 s38, s19, 16
	s_add_i32 s40, s18, 20
	s_add_i32 s41, s19, 20
	s_add_i32 s42, s18, 24
	s_add_i32 s43, s19, 24
	s_add_i32 s44, s18, 28
	s_add_i32 s45, s19, 28
	v_or_b32_e32 v16, s18, v3
	v_mad_u64_u32 v[14:15], s[26:27], v14, s87, v[8:9]
	v_or_b32_e32 v20, s21, v3
	v_or_b32_e32 v18, s28, v10
	v_or_b32_e32 v24, s29, v3
	v_or_b32_e32 v22, s31, v10
	v_or_b32_e32 v28, s35, v3
	v_or_b32_e32 v26, s36, v10
	v_or_b32_e32 v32, s37, v3
	v_or_b32_e32 v30, s38, v10
	v_or_b32_e32 v36, s40, v3
	v_or_b32_e32 v34, s41, v10
	v_or_b32_e32 v40, s42, v3
	v_or_b32_e32 v38, s43, v10
	v_or_b32_e32 v44, s44, v3
	v_or_b32_e32 v42, s45, v10
	v_mad_u64_u32 v[16:17], s[26:27], v16, s87, v[8:9]
	v_mad_u64_u32 v[18:19], s[26:27], v18, s87, v[8:9]
	v_mad_u64_u32 v[20:21], s[26:27], v20, s87, v[8:9]
	v_mad_u64_u32 v[22:23], s[26:27], v22, s87, v[8:9]
	v_mad_u64_u32 v[24:25], s[26:27], v24, s87, v[8:9]
	v_mad_u64_u32 v[26:27], s[26:27], v26, s87, v[8:9]
	v_mad_u64_u32 v[28:29], s[26:27], v28, s87, v[8:9]
	v_mad_u64_u32 v[30:31], s[26:27], v30, s87, v[8:9]
	v_mad_u64_u32 v[32:33], s[26:27], v32, s87, v[8:9]
	v_mad_u64_u32 v[34:35], s[26:27], v34, s87, v[8:9]
	v_mad_u64_u32 v[36:37], s[26:27], v36, s87, v[8:9]
	v_mad_u64_u32 v[38:39], s[26:27], v38, s87, v[8:9]
	v_mad_u64_u32 v[40:41], s[26:27], v40, s87, v[8:9]
	v_mad_u64_u32 v[42:43], s[26:27], v42, s87, v[8:9]
	v_mad_u64_u32 v[44:45], s[26:27], v44, s87, v[8:9]
	global_load_dword v94, v[14:15], off
	global_load_dword v95, v[16:17], off
	global_load_dword v96, v[18:19], off
	global_load_dword v97, v[20:21], off
	global_load_dword v98, v[22:23], off
	global_load_dword v99, v[24:25], off
	global_load_dword v100, v[26:27], off
	global_load_dword v101, v[28:29], off
	global_load_dword v102, v[30:31], off
	global_load_dword v103, v[32:33], off
	global_load_dword v104, v[34:35], off
	global_load_dword v105, v[36:37], off
	global_load_dword v106, v[38:39], off
	global_load_dword v107, v[40:41], off
	global_load_dword v108, v[42:43], off
	global_load_dword v109, v[44:45], off
	s_waitcnt vmcnt(31)
; #define LDS_WAIT() asm volatile("s_waitcnt lgkmcnt(0)" ::: "memory")
; __device__ __forceinline__ void transpose_item(const float* W, int K, int N, bf16* WT, bool upmap, LAS float* scr, int item, int lane) {
;     ...
;     if (upmap) { const int f = n0 < DFF ? n0 : n0 - DFF; d0 = (f >> 7) * 256 + (f & 127) + (n0 < DFF ? 0 : 128); }
; #pragma unroll 8
;     for (int i = 0; i < 32; ++i) { const int kk = 2 * i + (lane >> 5); scr[kk * 33 + (lane & 31)] = W[(size_t)(k0 + kk) * N + n0 + (lane & 31)]; }
;     LDS_WAIT(); asm volatile("" ::: "memory");
	ds_write_b32 v62, v46
	s_waitcnt vmcnt(30)
	ds_write_b32 v64, v47
	s_waitcnt vmcnt(29)
	ds_write_b32 v66, v48
	s_waitcnt vmcnt(28)
	ds_write_b32 v68, v49
	s_waitcnt vmcnt(27)
	ds_write_b32 v70, v50
	s_waitcnt vmcnt(26)
	ds_write_b32 v72, v51
	s_waitcnt vmcnt(25)
	ds_write_b32 v74, v52
	s_waitcnt vmcnt(24)
	ds_write_b32 v76, v53
	s_waitcnt vmcnt(23)
	ds_write_b32 v78, v54
	s_waitcnt vmcnt(22)
	ds_write_b32 v80, v55
	s_waitcnt vmcnt(21)
	ds_write_b32 v82, v56
	s_waitcnt vmcnt(20)
	ds_write_b32 v84, v57
	s_waitcnt vmcnt(19)
	ds_write_b32 v86, v58
	s_waitcnt vmcnt(18)
	ds_write_b32 v88, v59
	s_waitcnt vmcnt(17)
	ds_write_b32 v90, v60
	s_waitcnt vmcnt(16)
	ds_write_b32 v92, v61
	v_or_b32_e32 v16, s18, v1
	v_or_b32_e32 v14, s19, v0
	s_add_i32 s16, s16, 16
	s_add_i32 s13, s13, 16
	s_add_i32 s20, s20, -16
	v_mad_u64_u32 v[14:15], s[26:27], v14, s81, v[4:5]
	v_mad_u64_u32 v[16:17], s[26:27], v16, s81, v[4:5]
	v_or_b32_e32 v15, s21, v1
	v_or_b32_e32 v17, s28, v0
	v_or_b32_e32 v24, s29, v1
	v_or_b32_e32 v22, s31, v0
	v_or_b32_e32 v28, s35, v1
	v_or_b32_e32 v26, s36, v0
	v_or_b32_e32 v32, s37, v1
	v_or_b32_e32 v30, s38, v0
	v_or_b32_e32 v36, s40, v1
	v_or_b32_e32 v34, s41, v0
	v_or_b32_e32 v40, s42, v1
	v_or_b32_e32 v38, s43, v0
	v_or_b32_e32 v44, s44, v1
	v_or_b32_e32 v42, s45, v0
	s_cmp_lg_u32 s20, 0
	v_mad_u64_u32 v[18:19], s[26:27], v17, s81, v[4:5]
	v_mad_u64_u32 v[20:21], s[26:27], v15, s81, v[4:5]
	v_mad_u64_u32 v[22:23], s[26:27], v22, s81, v[4:5]
	v_mad_u64_u32 v[24:25], s[26:27], v24, s81, v[4:5]
	v_mad_u64_u32 v[26:27], s[26:27], v26, s81, v[4:5]
	v_mad_u64_u32 v[28:29], s[26:27], v28, s81, v[4:5]
	v_mad_u64_u32 v[30:31], s[26:27], v30, s81, v[4:5]
	v_mad_u64_u32 v[32:33], s[26:27], v32, s81, v[4:5]
	v_mad_u64_u32 v[34:35], s[26:27], v34, s81, v[4:5]
	v_mad_u64_u32 v[36:37], s[26:27], v36, s81, v[4:5]
	v_mad_u64_u32 v[38:39], s[26:27], v38, s81, v[4:5]
	v_mad_u64_u32 v[40:41], s[26:27], v40, s81, v[4:5]
	v_mad_u64_u32 v[42:43], s[26:27], v42, s81, v[4:5]
	v_mad_u64_u32 v[44:45], s[26:27], v44, s81, v[4:5]
	s_waitcnt vmcnt(15)
	ds_write_b32 v14, v94
	s_waitcnt vmcnt(14)
	ds_write_b32 v16, v95
	s_waitcnt vmcnt(13)
	ds_write_b32 v18, v96
	s_waitcnt vmcnt(12)
	ds_write_b32 v20, v97
	s_waitcnt vmcnt(11)
	ds_write_b32 v22, v98
	s_waitcnt vmcnt(10)
	ds_write_b32 v24, v99
	s_waitcnt vmcnt(9)
	ds_write_b32 v26, v100
	s_waitcnt vmcnt(8)
	ds_write_b32 v28, v101
	s_waitcnt vmcnt(7)
	ds_write_b32 v30, v102
	s_waitcnt vmcnt(6)
	ds_write_b32 v32, v103
	s_waitcnt vmcnt(5)
	ds_write_b32 v34, v104
	s_waitcnt vmcnt(4)
	ds_write_b32 v36, v105
	s_waitcnt vmcnt(3)
	ds_write_b32 v38, v106
	s_waitcnt vmcnt(2)
	ds_write_b32 v40, v107
	s_waitcnt vmcnt(1)
	ds_write_b32 v42, v108
	s_waitcnt vmcnt(0)
	ds_write_b32 v44, v109
	s_and_b32 s12, 0xffff, s12
	s_waitcnt lgkmcnt(0)
	s_and_b32 s5, 0xffff, s5
	s_add_i32 s13, s12, 0xfffff500
	s_cmpk_lt_u32 s5, 0x58
	ds_read2_b32 v[8:9], v7 offset1:8
	s_cselect_b32 s5, s12, s13
	ds_read2_b32 v[20:21], v7 offset0:33 offset1:41
	s_cselect_b32 s12, 0, 0x80
	s_lshl_b32 s13, s5, 1
	s_and_b32 s5, s5, 0x60
	s_or_b32 s5, s5, s12
	s_and_b32 s12, s13, 0xffffff00
	s_and_b32 s4, 0xffff, s4
	ds_read2_b32 v[22:23], v7 offset0:66 offset1:74
	s_or_b32 s12, s5, s12
	s_lshl_b32 s4, s4, 1
	ds_read2_b32 v[24:25], v7 offset0:99 offset1:107
	s_add_u32 s4, s10, s4
	s_waitcnt lgkmcnt(3)
	v_bfe_u32 v3, v8, 16, 1
	s_addc_u32 s5, s9, 0
	v_lshlrev_b32_e32 v208, 1, v6
	v_add3_u32 v3, v8, v3, s33
	s_waitcnt lgkmcnt(2)
	v_bfe_u32 v8, v20, 16, 1
	ds_read2_b32 v[26:27], v7 offset0:132 offset1:140
	v_lshl_add_u64 v[14:15], s[4:5], 0, v[208:209]
	s_mov_b64 s[4:5], 0x1400000
	v_lshrrev_b32_e32 v3, 16, v3
	v_add3_u32 v8, v20, v8, s33
	ds_read2_b32 v[28:29], v7 offset0:165 offset1:173
	v_lshl_add_u64 v[18:19], v[14:15], 0, s[4:5]
	v_and_or_b32 v14, v8, s80, v3
	s_waitcnt lgkmcnt(3)
	v_bfe_u32 v3, v22, 16, 1
	v_add3_u32 v3, v22, v3, s33
	s_waitcnt lgkmcnt(2)
; #define GAS __attribute__((address_space(1)))
; #define LAS __attribute__((address_space(3)))
; #define LDS_WAIT() asm volatile("s_waitcnt lgkmcnt(0)" ::: "memory")
; __device__ __forceinline__ unsigned pk2(float lo, float hi) { return f2bf(lo) | (f2bf(hi) << 16); }
; __device__ __forceinline__ void transpose_item(const float* W, int K, int N, bf16* WT, bool upmap, LAS float* scr, int item, int lane) {
;     ...
;     const int c = lane & 7;
; #pragma unroll
;     for (int j = 0; j < 4; ++j) { const int n = (lane >> 3) + 8 * j; const LAS float* s = scr + (8 * c) * 33 + n;
;         v4u o; o.x = pk2(s[0 * 33], s[1 * 33]); o.y = pk2(s[2 * 33], s[3 * 33]); o.z = pk2(s[4 * 33], s[5 * 33]); o.w = pk2(s[6 * 33], s[7 * 33]);
;         *(GAS v4u*)(WT + (size_t)(d0 + n) * K + k0 + 8 * c) = o; }
;     LDS_WAIT(); asm volatile("" ::: "memory");
	v_bfe_u32 v8, v24, 16, 1
	ds_read2_b32 v[30:31], v7 offset0:198 offset1:206
	v_lshrrev_b32_e32 v3, 16, v3
	v_add3_u32 v8, v24, v8, s33
	ds_read2_b32 v[32:33], v7 offset0:231 offset1:239
	v_and_or_b32 v15, v8, s80, v3
	s_waitcnt lgkmcnt(3)
	v_bfe_u32 v3, v26, 16, 1
	v_add3_u32 v3, v26, v3, s33
	s_waitcnt lgkmcnt(2)
	v_bfe_u32 v8, v28, 16, 1
	v_lshrrev_b32_e32 v3, 16, v3
	v_add3_u32 v8, v28, v8, s33
	v_and_or_b32 v16, v8, s80, v3
	s_waitcnt lgkmcnt(1)
	v_bfe_u32 v3, v30, 16, 1
	v_add3_u32 v3, v30, v3, s33
	s_waitcnt lgkmcnt(0)
	v_bfe_u32 v8, v32, 16, 1
	v_lshrrev_b32_e32 v3, 16, v3
	v_add3_u32 v8, v32, v8, s33
	v_or_b32_e32 v34, s12, v5
	v_and_or_b32 v17, v8, s80, v3
	v_ashrrev_i32_e32 v35, 31, v34
	v_bfe_u32 v3, v9, 16, 1
	v_lshlrev_b64 v[34:35], 11, v[34:35]
	v_add3_u32 v3, v9, v3, s33
	v_bfe_u32 v8, v21, 16, 1
	v_lshl_add_u64 v[34:35], v[18:19], 0, v[34:35]
	v_lshrrev_b32_e32 v3, 16, v3
	v_add3_u32 v8, v21, v8, s33
	global_store_dwordx4 v[34:35], v[14:17], off
	ds_read2_b32 v[20:21], v7 offset0:16 offset1:24
	v_or_b32_e32 v34, s12, v12
	v_and_or_b32 v14, v8, s80, v3
	v_bfe_u32 v3, v23, 16, 1
	v_add3_u32 v3, v23, v3, s33
	v_bfe_u32 v8, v25, 16, 1
	v_lshrrev_b32_e32 v3, 16, v3
	v_add3_u32 v8, v25, v8, s33
	v_and_or_b32 v15, v8, s80, v3
	v_bfe_u32 v3, v27, 16, 1
	v_add3_u32 v3, v27, v3, s33
	v_bfe_u32 v8, v29, 16, 1
	v_lshrrev_b32_e32 v3, 16, v3
	v_add3_u32 v8, v29, v8, s33
	v_and_or_b32 v16, v8, s80, v3
	v_bfe_u32 v3, v31, 16, 1
	v_add3_u32 v3, v31, v3, s33
	v_bfe_u32 v8, v33, 16, 1
	v_lshrrev_b32_e32 v3, 16, v3
	v_add3_u32 v8, v33, v8, s33
	v_and_or_b32 v17, v8, s80, v3
	v_or_b32_e32 v8, s12, v11
	v_ashrrev_i32_e32 v9, 31, v8
	v_lshlrev_b64 v[8:9], 11, v[8:9]
	v_lshl_add_u64 v[8:9], v[18:19], 0, v[8:9]
	global_store_dwordx4 v[8:9], v[14:17], off
	ds_read2_b32 v[8:9], v7 offset0:49 offset1:57
	ds_read2_b32 v[22:23], v7 offset0:82 offset1:90
	ds_read2_b32 v[24:25], v7 offset0:115 offset1:123
	s_waitcnt lgkmcnt(3)
	v_bfe_u32 v3, v20, 16, 1
	v_add3_u32 v3, v20, v3, s33
	s_waitcnt lgkmcnt(2)
	v_bfe_u32 v10, v8, 16, 1
	ds_read2_b32 v[26:27], v7 offset0:148 offset1:156
	v_lshrrev_b32_e32 v3, 16, v3
	v_add3_u32 v8, v8, v10, s33
	ds_read2_b32 v[28:29], v7 offset0:181 offset1:189
	v_and_or_b32 v14, v8, s80, v3
	s_waitcnt lgkmcnt(3)
	v_bfe_u32 v3, v22, 16, 1
	v_add3_u32 v3, v22, v3, s33
	s_waitcnt lgkmcnt(2)
	v_bfe_u32 v8, v24, 16, 1
	ds_read2_b32 v[30:31], v7 offset0:214 offset1:222
	v_lshrrev_b32_e32 v3, 16, v3
	v_add3_u32 v8, v24, v8, s33
	ds_read2_b32 v[32:33], v7 offset0:247 offset1:255
	v_and_or_b32 v15, v8, s80, v3
	s_waitcnt lgkmcnt(3)
	v_bfe_u32 v3, v26, 16, 1
	v_add3_u32 v3, v26, v3, s33
	s_waitcnt lgkmcnt(2)
	v_bfe_u32 v8, v28, 16, 1
	v_lshrrev_b32_e32 v3, 16, v3
	v_add3_u32 v8, v28, v8, s33
	v_and_or_b32 v16, v8, s80, v3
	s_waitcnt lgkmcnt(1)
	v_bfe_u32 v3, v30, 16, 1
	v_add3_u32 v3, v30, v3, s33
	s_waitcnt lgkmcnt(0)
	v_bfe_u32 v8, v32, 16, 1
	v_lshrrev_b32_e32 v3, 16, v3
	v_add3_u32 v8, v32, v8, s33
	v_and_or_b32 v17, v8, s80, v3
	v_ashrrev_i32_e32 v35, 31, v34
	v_bfe_u32 v3, v21, 16, 1
	v_lshlrev_b64 v[34:35], 11, v[34:35]
	v_add3_u32 v3, v21, v3, s33
	v_bfe_u32 v8, v9, 16, 1
	v_lshl_add_u64 v[34:35], v[18:19], 0, v[34:35]
	v_lshrrev_b32_e32 v3, 16, v3
	v_add3_u32 v8, v9, v8, s33
	global_store_dwordx4 v[34:35], v[14:17], off
	v_readlane_b32 s42, v254, 31
	v_readlane_b32 s43, v254, 32
	v_and_or_b32 v14, v8, s80, v3
	v_bfe_u32 v3, v23, 16, 1
	v_add3_u32 v3, v23, v3, s33
	v_bfe_u32 v8, v25, 16, 1
	v_lshrrev_b32_e32 v3, 16, v3
	v_add3_u32 v8, v25, v8, s33
	v_and_or_b32 v15, v8, s80, v3
	v_bfe_u32 v3, v27, 16, 1
	v_add3_u32 v3, v27, v3, s33
	v_bfe_u32 v8, v29, 16, 1
	v_lshrrev_b32_e32 v3, 16, v3
	v_add3_u32 v8, v29, v8, s33
	v_and_or_b32 v16, v8, s80, v3
	v_bfe_u32 v3, v31, 16, 1
	v_add3_u32 v3, v31, v3, s33
	v_bfe_u32 v8, v33, 16, 1
	v_lshrrev_b32_e32 v3, 16, v3
	v_add3_u32 v8, v33, v8, s33
	v_and_or_b32 v17, v8, s80, v3
	v_or_b32_e32 v8, s12, v13
	v_ashrrev_i32_e32 v9, 31, v8
	v_lshlrev_b64 v[8:9], 11, v[8:9]
	v_lshl_add_u64 v[8:9], v[18:19], 0, v[8:9]
	global_store_dwordx4 v[8:9], v[14:17], off
	s_waitcnt lgkmcnt(0)

; #define LAS __attribute__((address_space(3)))
; #define LDS_WAIT() asm volatile("s_waitcnt lgkmcnt(0)" ::: "memory")
; __device__ __forceinline__ void transpose_item(const float* W, int K, int N, bf16* WT, bool upmap, LAS float* scr, int item, int lane) {
;     const int nblk = N / 32, kb = item / nblk, nb = item % nblk, k0 = 64 * kb, n0 = 32 * nb;
;     int d0 = n0;
;     if (upmap) { const int f = n0 < DFF ? n0 : n0 - DFF; d0 = (f >> 7) * 256 + (f & 127) + (n0 < DFF ? 0 : 128); }
; #pragma unroll 8
;     for (int i = 0; i < 32; ++i) { const int kk = 2 * i + (lane >> 5); scr[kk * 33 + (lane & 31)] = W[(size_t)(k0 + kk) * N + n0 + (lane & 31)]; }
;     LDS_WAIT(); asm volatile("" ::: "memory");
.LBB0_426:
	s_lshl_b32 s20, s5, 1
	s_lshl_b32 s21, s13, 1
	v_or_b32_e32 v208, s21, v10
	s_add_i32 s18, s20, 4
	s_add_i32 s19, s21, 4
	v_mov_b32_e32 v17, v209
	s_add_i32 s27, s21, 8
	v_lshlrev_b64 v[30:31], 12, v[208:209]
	v_or_b32_e32 v16, s18, v3
	v_or_b32_e32 v208, s19, v10
	v_mov_b32_e32 v15, v209
	v_or_b32_e32 v14, s20, v3
	s_add_i32 s29, s21, 12
	v_lshlrev_b64 v[16:17], 12, v[16:17]
	v_lshlrev_b64 v[32:33], 12, v[208:209]
	v_or_b32_e32 v208, s27, v10
	s_add_i32 s26, s20, 8
	s_add_i32 s28, s20, 12
	s_add_i32 s35, s21, 16
	v_lshlrev_b64 v[14:15], 12, v[14:15]
	v_lshl_add_u64 v[30:31], v[8:9], 0, v[30:31]
	v_lshl_add_u64 v[16:17], v[8:9], 0, v[16:17]
	v_lshlrev_b64 v[34:35], 12, v[208:209]
	v_or_b32_e32 v208, s29, v10
	v_mov_b32_e32 v19, v209
	v_mov_b32_e32 v21, v209
	s_add_i32 s37, s21, 20
	v_or_b32_e32 v18, s26, v3
	v_or_b32_e32 v20, s28, v3
	v_lshl_add_u64 v[14:15], v[8:9], 0, v[14:15]
	v_lshl_add_u64 v[32:33], v[8:9], 0, v[32:33]
	global_load_dword v46, v[30:31], off
	global_load_dword v47, v[14:15], off
	global_load_dword v48, v[32:33], off
	global_load_dword v49, v[16:17], off
	v_lshlrev_b64 v[16:17], 12, v[208:209]
	v_or_b32_e32 v208, s35, v10
	s_add_i32 s31, s20, 16
	s_add_i32 s36, s20, 20
	s_add_i32 s40, s21, 24
	v_lshlrev_b64 v[18:19], 12, v[18:19]
	v_lshlrev_b64 v[20:21], 12, v[20:21]
	v_lshl_add_u64 v[14:15], v[8:9], 0, v[34:35]
	v_lshl_add_u64 v[16:17], v[8:9], 0, v[16:17]
	v_lshlrev_b64 v[30:31], 12, v[208:209]
	v_or_b32_e32 v208, s37, v10
	v_mov_b32_e32 v23, v209
	v_mov_b32_e32 v25, v209
	s_add_i32 s38, s20, 24
	s_add_i32 s41, s20, 28
	s_add_i32 s42, s21, 28
	v_or_b32_e32 v22, s31, v3
	v_or_b32_e32 v24, s36, v3
	v_lshl_add_u64 v[18:19], v[8:9], 0, v[18:19]
	v_lshl_add_u64 v[20:21], v[8:9], 0, v[20:21]
	global_load_dword v50, v[14:15], off
	global_load_dword v51, v[18:19], off
	global_load_dword v52, v[16:17], off
	global_load_dword v53, v[20:21], off
	v_lshlrev_b64 v[16:17], 12, v[208:209]
	v_or_b32_e32 v208, s40, v10
	v_mov_b32_e32 v27, v209
	v_mov_b32_e32 v29, v209
	v_or_b32_e32 v26, s38, v3
	v_or_b32_e32 v28, s41, v3
	v_lshlrev_b64 v[22:23], 12, v[22:23]
	v_lshlrev_b64 v[24:25], 12, v[24:25]
	v_lshl_add_u64 v[14:15], v[8:9], 0, v[30:31]
	v_lshl_add_u64 v[16:17], v[8:9], 0, v[16:17]
	v_lshlrev_b64 v[18:19], 12, v[208:209]
	v_or_b32_e32 v208, s42, v10
	v_lshlrev_b64 v[26:27], 12, v[26:27]
	v_lshlrev_b64 v[28:29], 12, v[28:29]
	v_lshl_add_u64 v[22:23], v[8:9], 0, v[22:23]
	v_lshl_add_u64 v[24:25], v[8:9], 0, v[24:25]
	global_load_dword v54, v[14:15], off
	global_load_dword v55, v[22:23], off
	global_load_dword v56, v[16:17], off
	global_load_dword v57, v[24:25], off
	v_lshl_add_u64 v[14:15], v[8:9], 0, v[18:19]
	v_lshlrev_b64 v[16:17], 12, v[208:209]
	v_lshl_add_u64 v[26:27], v[8:9], 0, v[26:27]
	v_lshl_add_u64 v[28:29], v[8:9], 0, v[28:29]
	v_lshl_add_u64 v[16:17], v[8:9], 0, v[16:17]
	global_load_dword v58, v[14:15], off
	global_load_dword v59, v[26:27], off
	global_load_dword v60, v[16:17], off
	global_load_dword v61, v[28:29], off
	v_or_b32_e32 v64, s20, v1
	v_or_b32_e32 v62, s21, v0
	s_add_i32 s13, s13, 16
	s_add_i32 s5, s5, 16
	s_add_i32 s16, s16, -16
	v_mad_u64_u32 v[62:63], s[20:21], v62, s81, v[4:5]
	v_mad_u64_u32 v[64:65], s[20:21], v64, s81, v[4:5]
	v_or_b32_e32 v63, s18, v1
	v_or_b32_e32 v65, s19, v0
	v_or_b32_e32 v72, s26, v1
	v_or_b32_e32 v70, s27, v0
	v_or_b32_e32 v76, s28, v1
	v_or_b32_e32 v74, s29, v0
	v_or_b32_e32 v80, s31, v1
	v_or_b32_e32 v78, s35, v0
	v_or_b32_e32 v84, s36, v1
	v_or_b32_e32 v82, s37, v0
	v_or_b32_e32 v88, s38, v1
	v_or_b32_e32 v86, s40, v0
	v_or_b32_e32 v92, s41, v1
	v_or_b32_e32 v90, s42, v0
	s_cmp_lg_u32 s16, 0
	v_mad_u64_u32 v[66:67], s[20:21], v65, s81, v[4:5]
	v_mad_u64_u32 v[68:69], s[20:21], v63, s81, v[4:5]
	v_mad_u64_u32 v[70:71], s[20:21], v70, s81, v[4:5]
	v_mad_u64_u32 v[72:73], s[20:21], v72, s81, v[4:5]
	v_mad_u64_u32 v[74:75], s[20:21], v74, s81, v[4:5]
	v_mad_u64_u32 v[76:77], s[20:21], v76, s81, v[4:5]
	v_mad_u64_u32 v[78:79], s[20:21], v78, s81, v[4:5]
	v_mad_u64_u32 v[80:81], s[20:21], v80, s81, v[4:5]
	v_mad_u64_u32 v[82:83], s[20:21], v82, s81, v[4:5]
	v_mad_u64_u32 v[84:85], s[20:21], v84, s81, v[4:5]
	v_mad_u64_u32 v[86:87], s[20:21], v86, s81, v[4:5]
	v_mad_u64_u32 v[88:89], s[20:21], v88, s81, v[4:5]
	v_mad_u64_u32 v[90:91], s[20:21], v90, s81, v[4:5]
	v_mad_u64_u32 v[92:93], s[20:21], v92, s81, v[4:5]
	s_lshl_b32 s20, s5, 1
	s_lshl_b32 s21, s13, 1
	v_or_b32_e32 v208, s21, v10
	s_add_i32 s18, s20, 4
	s_add_i32 s19, s21, 4
	v_mov_b32_e32 v17, v209
	s_add_i32 s27, s21, 8
	v_lshlrev_b64 v[30:31], 12, v[208:209]
	v_or_b32_e32 v16, s18, v3
	v_or_b32_e32 v208, s19, v10
	v_mov_b32_e32 v15, v209
	v_or_b32_e32 v14, s20, v3
	s_add_i32 s29, s21, 12
	v_lshlrev_b64 v[16:17], 12, v[16:17]
	v_lshlrev_b64 v[32:33], 12, v[208:209]
	v_or_b32_e32 v208, s27, v10
	s_add_i32 s26, s20, 8
	s_add_i32 s28, s20, 12
	s_add_i32 s35, s21, 16
	v_lshlrev_b64 v[14:15], 12, v[14:15]
	v_lshl_add_u64 v[30:31], v[8:9], 0, v[30:31]
	v_lshl_add_u64 v[16:17], v[8:9], 0, v[16:17]
	v_lshlrev_b64 v[34:35], 12, v[208:209]
	v_or_b32_e32 v208, s29, v10
	v_mov_b32_e32 v19, v209
	v_mov_b32_e32 v21, v209
	s_add_i32 s37, s21, 20
	v_or_b32_e32 v18, s26, v3
	v_or_b32_e32 v20, s28, v3
	v_lshl_add_u64 v[14:15], v[8:9], 0, v[14:15]
	v_lshl_add_u64 v[32:33], v[8:9], 0, v[32:33]
	global_load_dword v94, v[30:31], off
	global_load_dword v95, v[14:15], off
	global_load_dword v96, v[32:33], off
	global_load_dword v97, v[16:17], off
	v_lshlrev_b64 v[16:17], 12, v[208:209]
	v_or_b32_e32 v208, s35, v10
	s_add_i32 s31, s20, 16
	s_add_i32 s36, s20, 20
	s_add_i32 s40, s21, 24
	v_lshlrev_b64 v[18:19], 12, v[18:19]
; #define LDS_WAIT() asm volatile("s_waitcnt lgkmcnt(0)" ::: "memory")
; __device__ __forceinline__ void transpose_item(const float* W, int K, int N, bf16* WT, bool upmap, LAS float* scr, int item, int lane) {
;     ...
; #pragma unroll 8
;     for (int i = 0; i < 32; ++i) { const int kk = 2 * i + (lane >> 5); scr[kk * 33 + (lane & 31)] = W[(size_t)(k0 + kk) * N + n0 + (lane & 31)]; }
;     LDS_WAIT(); asm volatile("" ::: "memory");
	v_lshlrev_b64 v[20:21], 12, v[20:21]
	v_lshl_add_u64 v[14:15], v[8:9], 0, v[34:35]
	v_lshl_add_u64 v[16:17], v[8:9], 0, v[16:17]
	v_lshlrev_b64 v[30:31], 12, v[208:209]
	v_or_b32_e32 v208, s37, v10
	v_mov_b32_e32 v23, v209
	v_mov_b32_e32 v25, v209
	s_add_i32 s38, s20, 24
	s_add_i32 s41, s20, 28
	s_add_i32 s42, s21, 28
	v_or_b32_e32 v22, s31, v3
	v_or_b32_e32 v24, s36, v3
	v_lshl_add_u64 v[18:19], v[8:9], 0, v[18:19]
	v_lshl_add_u64 v[20:21], v[8:9], 0, v[20:21]
	global_load_dword v98, v[14:15], off
	global_load_dword v99, v[18:19], off
	global_load_dword v100, v[16:17], off
	global_load_dword v101, v[20:21], off
	v_lshlrev_b64 v[16:17], 12, v[208:209]
	v_or_b32_e32 v208, s40, v10
	v_mov_b32_e32 v27, v209
	v_mov_b32_e32 v29, v209
	v_or_b32_e32 v26, s38, v3
	v_or_b32_e32 v28, s41, v3
	v_lshlrev_b64 v[22:23], 12, v[22:23]
	v_lshlrev_b64 v[24:25], 12, v[24:25]
	v_lshl_add_u64 v[14:15], v[8:9], 0, v[30:31]
	v_lshl_add_u64 v[16:17], v[8:9], 0, v[16:17]
	v_lshlrev_b64 v[18:19], 12, v[208:209]
	v_or_b32_e32 v208, s42, v10
	v_lshlrev_b64 v[26:27], 12, v[26:27]
	v_lshlrev_b64 v[28:29], 12, v[28:29]
	v_lshl_add_u64 v[22:23], v[8:9], 0, v[22:23]
	v_lshl_add_u64 v[24:25], v[8:9], 0, v[24:25]
	global_load_dword v102, v[14:15], off
	global_load_dword v103, v[22:23], off
	global_load_dword v104, v[16:17], off
	global_load_dword v105, v[24:25], off
	v_lshl_add_u64 v[14:15], v[8:9], 0, v[18:19]
	v_lshlrev_b64 v[16:17], 12, v[208:209]
	v_lshl_add_u64 v[26:27], v[8:9], 0, v[26:27]
	v_lshl_add_u64 v[28:29], v[8:9], 0, v[28:29]
	v_lshl_add_u64 v[16:17], v[8:9], 0, v[16:17]
	global_load_dword v106, v[14:15], off
	global_load_dword v107, v[26:27], off
	global_load_dword v108, v[16:17], off
	global_load_dword v109, v[28:29], off
	s_waitcnt vmcnt(31)
	ds_write_b32 v62, v46
	s_waitcnt vmcnt(30)
	ds_write_b32 v64, v47
	s_waitcnt vmcnt(29)
	ds_write_b32 v66, v48
	s_waitcnt vmcnt(28)
	ds_write_b32 v68, v49
	s_waitcnt vmcnt(27)
	ds_write_b32 v70, v50
	s_waitcnt vmcnt(26)
	ds_write_b32 v72, v51
	s_waitcnt vmcnt(25)
	ds_write_b32 v74, v52
	s_waitcnt vmcnt(24)
	ds_write_b32 v76, v53
	s_waitcnt vmcnt(23)
	ds_write_b32 v78, v54
	s_waitcnt vmcnt(22)
	ds_write_b32 v80, v55
	s_waitcnt vmcnt(21)
	ds_write_b32 v82, v56
	s_waitcnt vmcnt(20)
	ds_write_b32 v84, v57
	s_waitcnt vmcnt(19)
	ds_write_b32 v86, v58
	s_waitcnt vmcnt(18)
	ds_write_b32 v88, v59
	s_waitcnt vmcnt(17)
	ds_write_b32 v90, v60
	s_waitcnt vmcnt(16)
	ds_write_b32 v92, v61
	v_or_b32_e32 v16, s20, v1
	v_or_b32_e32 v14, s21, v0
	s_add_i32 s13, s13, 16
	s_add_i32 s5, s5, 16
	s_add_i32 s16, s16, -16
	v_mad_u64_u32 v[14:15], s[20:21], v14, s81, v[4:5]
	v_mad_u64_u32 v[16:17], s[20:21], v16, s81, v[4:5]
	v_or_b32_e32 v15, s18, v1
	v_or_b32_e32 v17, s19, v0
	v_or_b32_e32 v24, s26, v1
	v_or_b32_e32 v22, s27, v0
	v_or_b32_e32 v28, s28, v1
	v_or_b32_e32 v26, s29, v0
	v_or_b32_e32 v32, s31, v1
	v_or_b32_e32 v30, s35, v0
	v_or_b32_e32 v36, s36, v1
	v_or_b32_e32 v34, s37, v0
	v_or_b32_e32 v40, s38, v1
	v_or_b32_e32 v38, s40, v0
	v_or_b32_e32 v44, s41, v1
	v_or_b32_e32 v42, s42, v0
	s_cmp_lg_u32 s16, 0
	v_mad_u64_u32 v[18:19], s[20:21], v17, s81, v[4:5]
	v_mad_u64_u32 v[20:21], s[20:21], v15, s81, v[4:5]
	v_mad_u64_u32 v[22:23], s[20:21], v22, s81, v[4:5]
	v_mad_u64_u32 v[24:25], s[20:21], v24, s81, v[4:5]
	v_mad_u64_u32 v[26:27], s[20:21], v26, s81, v[4:5]
	v_mad_u64_u32 v[28:29], s[20:21], v28, s81, v[4:5]
	v_mad_u64_u32 v[30:31], s[20:21], v30, s81, v[4:5]
	v_mad_u64_u32 v[32:33], s[20:21], v32, s81, v[4:5]
	v_mad_u64_u32 v[34:35], s[20:21], v34, s81, v[4:5]
	v_mad_u64_u32 v[36:37], s[20:21], v36, s81, v[4:5]
	v_mad_u64_u32 v[38:39], s[20:21], v38, s81, v[4:5]
	v_mad_u64_u32 v[40:41], s[20:21], v40, s81, v[4:5]
	v_mad_u64_u32 v[42:43], s[20:21], v42, s81, v[4:5]
	v_mad_u64_u32 v[44:45], s[20:21], v44, s81, v[4:5]
	s_waitcnt vmcnt(15)
	ds_write_b32 v14, v94
	s_waitcnt vmcnt(14)
	ds_write_b32 v16, v95
	s_waitcnt vmcnt(13)
	ds_write_b32 v18, v96
	s_waitcnt vmcnt(12)
	ds_write_b32 v20, v97
	s_waitcnt vmcnt(11)
	ds_write_b32 v22, v98
	s_waitcnt vmcnt(10)
	ds_write_b32 v24, v99
	s_waitcnt vmcnt(9)
	ds_write_b32 v26, v100
	s_waitcnt vmcnt(8)
	ds_write_b32 v28, v101
	s_waitcnt vmcnt(7)
	ds_write_b32 v30, v102
	s_waitcnt vmcnt(6)
	ds_write_b32 v32, v103
	s_waitcnt vmcnt(5)
	ds_write_b32 v34, v104
	s_waitcnt vmcnt(4)
	ds_write_b32 v36, v105
	s_waitcnt vmcnt(3)
	ds_write_b32 v38, v106
	s_waitcnt vmcnt(2)
	ds_write_b32 v40, v107
	s_waitcnt vmcnt(1)
	ds_write_b32 v42, v108
	s_waitcnt vmcnt(0)
	ds_write_b32 v44, v109
	s_waitcnt lgkmcnt(0)
	ds_read2_b32 v[8:9], v7 offset1:8
	ds_read2_b32 v[20:21], v7 offset0:33 offset1:41
	ds_read2_b32 v[22:23], v7 offset0:66 offset1:74
	s_lshl_b32 s5, s12, 1
	ds_read2_b32 v[24:25], v7 offset0:99 offset1:107
	s_add_u32 s12, s10, s5
	s_waitcnt lgkmcnt(3)
; #define GAS __attribute__((address_space(1)))
; #define LAS __attribute__((address_space(3)))
; #define LDS_WAIT() asm volatile("s_waitcnt lgkmcnt(0)" ::: "memory")
; __device__ __forceinline__ unsigned pk2(float lo, float hi) { return f2bf(lo) | (f2bf(hi) << 16); }
; __device__ __forceinline__ void transpose_item(const float* W, int K, int N, bf16* WT, bool upmap, LAS float* scr, int item, int lane) {
;     ...
;     const int c = lane & 7;
; #pragma unroll
;     for (int j = 0; j < 4; ++j) { const int n = (lane >> 3) + 8 * j; const LAS float* s = scr + (8 * c) * 33 + n;
;         v4u o; o.x = pk2(s[0 * 33], s[1 * 33]); o.y = pk2(s[2 * 33], s[3 * 33]); o.z = pk2(s[4 * 33], s[5 * 33]); o.w = pk2(s[6 * 33], s[7 * 33]);
;         *(GAS v4u*)(WT + (size_t)(d0 + n) * K + k0 + 8 * c) = o; }
;     LDS_WAIT(); asm volatile("" ::: "memory");
	v_bfe_u32 v3, v8, 16, 1
	s_addc_u32 s13, s9, 0
	v_lshlrev_b32_e32 v208, 1, v6
	v_add3_u32 v3, v8, v3, s33
	s_waitcnt lgkmcnt(2)
	v_bfe_u32 v8, v20, 16, 1
	ds_read2_b32 v[26:27], v7 offset0:132 offset1:140
	v_lshl_add_u64 v[14:15], s[12:13], 0, v[208:209]
	s_mov_b64 s[12:13], 0x1200000
	v_lshrrev_b32_e32 v3, 16, v3
	v_add3_u32 v8, v20, v8, s33
	ds_read2_b32 v[28:29], v7 offset0:165 offset1:173
	v_lshl_add_u64 v[18:19], v[14:15], 0, s[12:13]
	v_and_or_b32 v14, v8, s80, v3
	s_waitcnt lgkmcnt(3)
	v_bfe_u32 v3, v22, 16, 1
	v_add3_u32 v3, v22, v3, s33
	s_waitcnt lgkmcnt(2)
	v_bfe_u32 v8, v24, 16, 1
	ds_read2_b32 v[30:31], v7 offset0:198 offset1:206
	v_lshrrev_b32_e32 v3, 16, v3
	v_add3_u32 v8, v24, v8, s33
	ds_read2_b32 v[32:33], v7 offset0:231 offset1:239
	v_and_or_b32 v15, v8, s80, v3
	s_waitcnt lgkmcnt(3)
	v_bfe_u32 v3, v26, 16, 1
	v_add3_u32 v3, v26, v3, s33
	s_waitcnt lgkmcnt(2)
	v_bfe_u32 v8, v28, 16, 1
	v_lshrrev_b32_e32 v3, 16, v3
	v_add3_u32 v8, v28, v8, s33
	v_and_or_b32 v16, v8, s80, v3
	s_waitcnt lgkmcnt(1)
	v_bfe_u32 v3, v30, 16, 1
	v_add3_u32 v3, v30, v3, s33
	s_waitcnt lgkmcnt(0)
	v_bfe_u32 v8, v32, 16, 1
	v_lshrrev_b32_e32 v3, 16, v3
	v_add3_u32 v8, v32, v8, s33
	v_and_or_b32 v17, v8, s80, v3
	v_or_b32_e32 v3, s4, v5
	v_lshlrev_b32_e32 v208, 11, v3
	v_bfe_u32 v3, v9, 16, 1
	v_add3_u32 v3, v9, v3, s33
	v_bfe_u32 v8, v21, 16, 1
	v_lshl_add_u64 v[34:35], v[18:19], 0, v[208:209]
	v_lshrrev_b32_e32 v3, 16, v3
	v_add3_u32 v8, v21, v8, s33
	global_store_dwordx4 v[34:35], v[14:17], off
	v_readlane_b32 s42, v254, 31
	v_readlane_b32 s43, v254, 32
	v_and_or_b32 v14, v8, s80, v3
	v_bfe_u32 v3, v23, 16, 1
	v_add3_u32 v3, v23, v3, s33
	v_bfe_u32 v8, v25, 16, 1
	v_lshrrev_b32_e32 v3, 16, v3
	v_add3_u32 v8, v25, v8, s33
	v_and_or_b32 v15, v8, s80, v3
	v_bfe_u32 v3, v27, 16, 1
	v_add3_u32 v3, v27, v3, s33
	v_bfe_u32 v8, v29, 16, 1
	v_lshrrev_b32_e32 v3, 16, v3
	v_add3_u32 v8, v29, v8, s33
	v_and_or_b32 v16, v8, s80, v3
	v_bfe_u32 v3, v31, 16, 1
	v_add3_u32 v3, v31, v3, s33
	v_bfe_u32 v8, v33, 16, 1
	v_lshrrev_b32_e32 v3, 16, v3
	v_add3_u32 v8, v33, v8, s33
	v_and_or_b32 v17, v8, s80, v3
	v_or_b32_e32 v3, s4, v11
	v_lshlrev_b32_e32 v208, 11, v3
	ds_read2_b32 v[8:9], v7 offset0:16 offset1:24
	v_lshl_add_u64 v[20:21], v[18:19], 0, v[208:209]
	global_store_dwordx4 v[20:21], v[14:17], off
	ds_read2_b32 v[20:21], v7 offset0:49 offset1:57
	ds_read2_b32 v[22:23], v7 offset0:82 offset1:90
	ds_read2_b32 v[24:25], v7 offset0:115 offset1:123
	s_waitcnt lgkmcnt(3)
	v_bfe_u32 v3, v8, 16, 1
	v_add3_u32 v3, v8, v3, s33
	s_waitcnt lgkmcnt(2)
	v_bfe_u32 v8, v20, 16, 1
	ds_read2_b32 v[26:27], v7 offset0:148 offset1:156
	v_lshrrev_b32_e32 v3, 16, v3
	v_add3_u32 v8, v20, v8, s33
	ds_read2_b32 v[28:29], v7 offset0:181 offset1:189
	v_and_or_b32 v14, v8, s80, v3
	s_waitcnt lgkmcnt(3)
	v_bfe_u32 v3, v22, 16, 1
	v_add3_u32 v3, v22, v3, s33
	s_waitcnt lgkmcnt(2)
	v_bfe_u32 v8, v24, 16, 1
	ds_read2_b32 v[30:31], v7 offset0:214 offset1:222
	v_lshrrev_b32_e32 v3, 16, v3
	v_add3_u32 v8, v24, v8, s33
	ds_read2_b32 v[32:33], v7 offset0:247 offset1:255
	v_and_or_b32 v15, v8, s80, v3
	s_waitcnt lgkmcnt(3)
	v_bfe_u32 v3, v26, 16, 1
	v_add3_u32 v3, v26, v3, s33
	s_waitcnt lgkmcnt(2)
	v_bfe_u32 v8, v28, 16, 1
	v_lshrrev_b32_e32 v3, 16, v3
	v_add3_u32 v8, v28, v8, s33
	v_and_or_b32 v16, v8, s80, v3
	s_waitcnt lgkmcnt(1)
	v_bfe_u32 v3, v30, 16, 1
	v_add3_u32 v3, v30, v3, s33
	s_waitcnt lgkmcnt(0)
	v_bfe_u32 v8, v32, 16, 1
	v_lshrrev_b32_e32 v3, 16, v3
	v_add3_u32 v8, v32, v8, s33
	v_and_or_b32 v17, v8, s80, v3
	v_or_b32_e32 v3, s4, v12
	v_lshlrev_b32_e32 v208, 11, v3
	v_bfe_u32 v3, v9, 16, 1
	v_add3_u32 v3, v9, v3, s33
	v_bfe_u32 v8, v21, 16, 1
	v_lshl_add_u64 v[34:35], v[18:19], 0, v[208:209]
	v_lshrrev_b32_e32 v3, 16, v3
	v_add3_u32 v8, v21, v8, s33
	global_store_dwordx4 v[34:35], v[14:17], off
	s_nop 1
	v_and_or_b32 v14, v8, s80, v3
	v_bfe_u32 v3, v23, 16, 1
	v_add3_u32 v3, v23, v3, s33
	v_bfe_u32 v8, v25, 16, 1
	v_lshrrev_b32_e32 v3, 16, v3
	v_add3_u32 v8, v25, v8, s33
	v_and_or_b32 v15, v8, s80, v3
	v_bfe_u32 v3, v27, 16, 1
	v_add3_u32 v3, v27, v3, s33
	v_bfe_u32 v8, v29, 16, 1
	v_lshrrev_b32_e32 v3, 16, v3
	v_add3_u32 v8, v29, v8, s33
	v_and_or_b32 v16, v8, s80, v3
	v_bfe_u32 v3, v31, 16, 1
	v_add3_u32 v3, v31, v3, s33
	v_bfe_u32 v8, v33, 16, 1
	v_lshrrev_b32_e32 v3, 16, v3
	v_add3_u32 v8, v33, v8, s33
	v_and_or_b32 v17, v8, s80, v3
	v_or_b32_e32 v3, s4, v13
	v_lshlrev_b32_e32 v208, 11, v3
	v_lshl_add_u64 v[8:9], v[18:19], 0, v[208:209]
	global_store_dwordx4 v[8:9], v[14:17], off
	s_waitcnt lgkmcnt(0)

; #define LAS __attribute__((address_space(3)))
; #define LDS_WAIT() asm volatile("s_waitcnt lgkmcnt(0)" ::: "memory")
; __device__ __forceinline__ void transpose_item(const float* W, int K, int N, bf16* WT, bool upmap, LAS float* scr, int item, int lane) {
;     const int nblk = N / 32, kb = item / nblk, nb = item % nblk, k0 = 64 * kb, n0 = 32 * nb;
;     int d0 = n0;
;     if (upmap) { const int f = n0 < DFF ? n0 : n0 - DFF; d0 = (f >> 7) * 256 + (f & 127) + (n0 < DFF ? 0 : 128); }
; #pragma unroll 8
;     for (int i = 0; i < 32; ++i) { const int kk = 2 * i + (lane >> 5); scr[kk * 33 + (lane & 31)] = W[(size_t)(k0 + kk) * N + n0 + (lane & 31)]; }
;     LDS_WAIT(); asm volatile("" ::: "memory");
.LBB0_431:
	s_lshl_b32 s20, s5, 1
	s_lshl_b32 s21, s13, 1
	v_or_b32_e32 v208, s21, v10
	s_add_i32 s18, s20, 4
	s_add_i32 s19, s21, 4
	v_mov_b32_e32 v17, v209
	s_add_i32 s27, s21, 8
	v_lshlrev_b64 v[30:31], 12, v[208:209]
	v_or_b32_e32 v16, s18, v3
	v_or_b32_e32 v208, s19, v10
	v_mov_b32_e32 v15, v209
	v_or_b32_e32 v14, s20, v3
	s_add_i32 s29, s21, 12
	v_lshlrev_b64 v[16:17], 12, v[16:17]
	v_lshlrev_b64 v[32:33], 12, v[208:209]
	v_or_b32_e32 v208, s27, v10
	s_add_i32 s26, s20, 8
	s_add_i32 s28, s20, 12
	s_add_i32 s35, s21, 16
	v_lshlrev_b64 v[14:15], 12, v[14:15]
	v_lshl_add_u64 v[30:31], v[8:9], 0, v[30:31]
	v_lshl_add_u64 v[16:17], v[8:9], 0, v[16:17]
	v_lshlrev_b64 v[34:35], 12, v[208:209]
	v_or_b32_e32 v208, s29, v10
	v_mov_b32_e32 v19, v209
	v_mov_b32_e32 v21, v209
	s_add_i32 s37, s21, 20
	v_or_b32_e32 v18, s26, v3
	v_or_b32_e32 v20, s28, v3
	v_lshl_add_u64 v[14:15], v[8:9], 0, v[14:15]
	v_lshl_add_u64 v[32:33], v[8:9], 0, v[32:33]
	global_load_dword v46, v[30:31], off
	global_load_dword v47, v[14:15], off
	global_load_dword v48, v[32:33], off
	global_load_dword v49, v[16:17], off
	v_lshlrev_b64 v[16:17], 12, v[208:209]
	v_or_b32_e32 v208, s35, v10
	s_add_i32 s31, s20, 16
	s_add_i32 s36, s20, 20
	s_add_i32 s40, s21, 24
	v_lshlrev_b64 v[18:19], 12, v[18:19]
	v_lshlrev_b64 v[20:21], 12, v[20:21]
	v_lshl_add_u64 v[14:15], v[8:9], 0, v[34:35]
	v_lshl_add_u64 v[16:17], v[8:9], 0, v[16:17]
	v_lshlrev_b64 v[30:31], 12, v[208:209]
	v_or_b32_e32 v208, s37, v10
	v_mov_b32_e32 v23, v209
	v_mov_b32_e32 v25, v209
	s_add_i32 s38, s20, 24
	s_add_i32 s41, s20, 28
	s_add_i32 s42, s21, 28
	v_or_b32_e32 v22, s31, v3
	v_or_b32_e32 v24, s36, v3
	v_lshl_add_u64 v[18:19], v[8:9], 0, v[18:19]
	v_lshl_add_u64 v[20:21], v[8:9], 0, v[20:21]
	global_load_dword v50, v[14:15], off
	global_load_dword v51, v[18:19], off
	global_load_dword v52, v[16:17], off
	global_load_dword v53, v[20:21], off
	v_lshlrev_b64 v[16:17], 12, v[208:209]
	v_or_b32_e32 v208, s40, v10
	v_mov_b32_e32 v27, v209
	v_mov_b32_e32 v29, v209
	v_or_b32_e32 v26, s38, v3
	v_or_b32_e32 v28, s41, v3
	v_lshlrev_b64 v[22:23], 12, v[22:23]
	v_lshlrev_b64 v[24:25], 12, v[24:25]
	v_lshl_add_u64 v[14:15], v[8:9], 0, v[30:31]
	v_lshl_add_u64 v[16:17], v[8:9], 0, v[16:17]
	v_lshlrev_b64 v[18:19], 12, v[208:209]
	v_or_b32_e32 v208, s42, v10
	v_lshlrev_b64 v[26:27], 12, v[26:27]
	v_lshlrev_b64 v[28:29], 12, v[28:29]
	v_lshl_add_u64 v[22:23], v[8:9], 0, v[22:23]
	v_lshl_add_u64 v[24:25], v[8:9], 0, v[24:25]
	global_load_dword v54, v[14:15], off
	global_load_dword v55, v[22:23], off
	global_load_dword v56, v[16:17], off
	global_load_dword v57, v[24:25], off
	v_lshl_add_u64 v[14:15], v[8:9], 0, v[18:19]
	v_lshlrev_b64 v[16:17], 12, v[208:209]
	v_lshl_add_u64 v[26:27], v[8:9], 0, v[26:27]
	v_lshl_add_u64 v[28:29], v[8:9], 0, v[28:29]
	v_lshl_add_u64 v[16:17], v[8:9], 0, v[16:17]
	global_load_dword v58, v[14:15], off
	global_load_dword v59, v[26:27], off
	global_load_dword v60, v[16:17], off
	global_load_dword v61, v[28:29], off
	v_or_b32_e32 v64, s20, v1
	v_or_b32_e32 v62, s21, v0
	s_add_i32 s13, s13, 16
	s_add_i32 s5, s5, 16
	s_add_i32 s16, s16, -16
	v_mad_u64_u32 v[62:63], s[20:21], v62, s81, v[4:5]
	v_mad_u64_u32 v[64:65], s[20:21], v64, s81, v[4:5]
	v_or_b32_e32 v63, s18, v1
	v_or_b32_e32 v65, s19, v0
	v_or_b32_e32 v72, s26, v1
	v_or_b32_e32 v70, s27, v0
	v_or_b32_e32 v76, s28, v1
	v_or_b32_e32 v74, s29, v0
	v_or_b32_e32 v80, s31, v1
	v_or_b32_e32 v78, s35, v0
	v_or_b32_e32 v84, s36, v1
	v_or_b32_e32 v82, s37, v0
	v_or_b32_e32 v88, s38, v1
	v_or_b32_e32 v86, s40, v0
	v_or_b32_e32 v92, s41, v1
	v_or_b32_e32 v90, s42, v0
	s_cmp_lg_u32 s16, 0
	v_mad_u64_u32 v[66:67], s[20:21], v65, s81, v[4:5]
	v_mad_u64_u32 v[68:69], s[20:21], v63, s81, v[4:5]
	v_mad_u64_u32 v[70:71], s[20:21], v70, s81, v[4:5]
	v_mad_u64_u32 v[72:73], s[20:21], v72, s81, v[4:5]
	v_mad_u64_u32 v[74:75], s[20:21], v74, s81, v[4:5]
	v_mad_u64_u32 v[76:77], s[20:21], v76, s81, v[4:5]
	v_mad_u64_u32 v[78:79], s[20:21], v78, s81, v[4:5]
	v_mad_u64_u32 v[80:81], s[20:21], v80, s81, v[4:5]
	v_mad_u64_u32 v[82:83], s[20:21], v82, s81, v[4:5]
	v_mad_u64_u32 v[84:85], s[20:21], v84, s81, v[4:5]
	v_mad_u64_u32 v[86:87], s[20:21], v86, s81, v[4:5]
	v_mad_u64_u32 v[88:89], s[20:21], v88, s81, v[4:5]
	v_mad_u64_u32 v[90:91], s[20:21], v90, s81, v[4:5]
	v_mad_u64_u32 v[92:93], s[20:21], v92, s81, v[4:5]
	s_lshl_b32 s20, s5, 1
	s_lshl_b32 s21, s13, 1
	v_or_b32_e32 v208, s21, v10
	s_add_i32 s18, s20, 4
	s_add_i32 s19, s21, 4
	v_mov_b32_e32 v17, v209
	s_add_i32 s27, s21, 8
	v_lshlrev_b64 v[30:31], 12, v[208:209]
	v_or_b32_e32 v16, s18, v3
	v_or_b32_e32 v208, s19, v10
	v_mov_b32_e32 v15, v209
	v_or_b32_e32 v14, s20, v3
	s_add_i32 s29, s21, 12
	v_lshlrev_b64 v[16:17], 12, v[16:17]
	v_lshlrev_b64 v[32:33], 12, v[208:209]
	v_or_b32_e32 v208, s27, v10
	s_add_i32 s26, s20, 8
	s_add_i32 s28, s20, 12
	s_add_i32 s35, s21, 16
	v_lshlrev_b64 v[14:15], 12, v[14:15]
	v_lshl_add_u64 v[30:31], v[8:9], 0, v[30:31]
	v_lshl_add_u64 v[16:17], v[8:9], 0, v[16:17]
	v_lshlrev_b64 v[34:35], 12, v[208:209]
	v_or_b32_e32 v208, s29, v10
	v_mov_b32_e32 v19, v209
	v_mov_b32_e32 v21, v209
	s_add_i32 s37, s21, 20
	v_or_b32_e32 v18, s26, v3
	v_or_b32_e32 v20, s28, v3
	v_lshl_add_u64 v[14:15], v[8:9], 0, v[14:15]
	v_lshl_add_u64 v[32:33], v[8:9], 0, v[32:33]
	global_load_dword v94, v[30:31], off
	global_load_dword v95, v[14:15], off
	global_load_dword v96, v[32:33], off
	global_load_dword v97, v[16:17], off
	v_lshlrev_b64 v[16:17], 12, v[208:209]
	v_or_b32_e32 v208, s35, v10
	s_add_i32 s31, s20, 16
	s_add_i32 s36, s20, 20
	s_add_i32 s40, s21, 24
	v_lshlrev_b64 v[18:19], 12, v[18:19]
; #define LDS_WAIT() asm volatile("s_waitcnt lgkmcnt(0)" ::: "memory")
; __device__ __forceinline__ void transpose_item(const float* W, int K, int N, bf16* WT, bool upmap, LAS float* scr, int item, int lane) {
;     ...
; #pragma unroll 8
;     for (int i = 0; i < 32; ++i) { const int kk = 2 * i + (lane >> 5); scr[kk * 33 + (lane & 31)] = W[(size_t)(k0 + kk) * N + n0 + (lane & 31)]; }
;     LDS_WAIT(); asm volatile("" ::: "memory");
	v_lshlrev_b64 v[20:21], 12, v[20:21]
	v_lshl_add_u64 v[14:15], v[8:9], 0, v[34:35]
	v_lshl_add_u64 v[16:17], v[8:9], 0, v[16:17]
	v_lshlrev_b64 v[30:31], 12, v[208:209]
	v_or_b32_e32 v208, s37, v10
	v_mov_b32_e32 v23, v209
	v_mov_b32_e32 v25, v209
	s_add_i32 s38, s20, 24
	s_add_i32 s41, s20, 28
	s_add_i32 s42, s21, 28
	v_or_b32_e32 v22, s31, v3
	v_or_b32_e32 v24, s36, v3
	v_lshl_add_u64 v[18:19], v[8:9], 0, v[18:19]
	v_lshl_add_u64 v[20:21], v[8:9], 0, v[20:21]
	global_load_dword v98, v[14:15], off
	global_load_dword v99, v[18:19], off
	global_load_dword v100, v[16:17], off
	global_load_dword v101, v[20:21], off
	v_lshlrev_b64 v[16:17], 12, v[208:209]
	v_or_b32_e32 v208, s40, v10
	v_mov_b32_e32 v27, v209
	v_mov_b32_e32 v29, v209
	v_or_b32_e32 v26, s38, v3
	v_or_b32_e32 v28, s41, v3
	v_lshlrev_b64 v[22:23], 12, v[22:23]
	v_lshlrev_b64 v[24:25], 12, v[24:25]
	v_lshl_add_u64 v[14:15], v[8:9], 0, v[30:31]
	v_lshl_add_u64 v[16:17], v[8:9], 0, v[16:17]
	v_lshlrev_b64 v[18:19], 12, v[208:209]
	v_or_b32_e32 v208, s42, v10
	v_lshlrev_b64 v[26:27], 12, v[26:27]
	v_lshlrev_b64 v[28:29], 12, v[28:29]
	v_lshl_add_u64 v[22:23], v[8:9], 0, v[22:23]
	v_lshl_add_u64 v[24:25], v[8:9], 0, v[24:25]
	global_load_dword v102, v[14:15], off
	global_load_dword v103, v[22:23], off
	global_load_dword v104, v[16:17], off
	global_load_dword v105, v[24:25], off
	v_lshl_add_u64 v[14:15], v[8:9], 0, v[18:19]
	v_lshlrev_b64 v[16:17], 12, v[208:209]
	v_lshl_add_u64 v[26:27], v[8:9], 0, v[26:27]
	v_lshl_add_u64 v[28:29], v[8:9], 0, v[28:29]
	v_lshl_add_u64 v[16:17], v[8:9], 0, v[16:17]
	global_load_dword v106, v[14:15], off
	global_load_dword v107, v[26:27], off
	global_load_dword v108, v[16:17], off
	global_load_dword v109, v[28:29], off
	s_waitcnt vmcnt(31)
	ds_write_b32 v62, v46
	s_waitcnt vmcnt(30)
	ds_write_b32 v64, v47
	s_waitcnt vmcnt(29)
	ds_write_b32 v66, v48
	s_waitcnt vmcnt(28)
	ds_write_b32 v68, v49
	s_waitcnt vmcnt(27)
	ds_write_b32 v70, v50
	s_waitcnt vmcnt(26)
	ds_write_b32 v72, v51
	s_waitcnt vmcnt(25)
	ds_write_b32 v74, v52
	s_waitcnt vmcnt(24)
	ds_write_b32 v76, v53
	s_waitcnt vmcnt(23)
	ds_write_b32 v78, v54
	s_waitcnt vmcnt(22)
	ds_write_b32 v80, v55
	s_waitcnt vmcnt(21)
	ds_write_b32 v82, v56
	s_waitcnt vmcnt(20)
	ds_write_b32 v84, v57
	s_waitcnt vmcnt(19)
	ds_write_b32 v86, v58
	s_waitcnt vmcnt(18)
	ds_write_b32 v88, v59
	s_waitcnt vmcnt(17)
	ds_write_b32 v90, v60
	s_waitcnt vmcnt(16)
	ds_write_b32 v92, v61
	v_or_b32_e32 v16, s20, v1
	v_or_b32_e32 v14, s21, v0
	s_add_i32 s13, s13, 16
	s_add_i32 s5, s5, 16
	s_add_i32 s16, s16, -16
	v_mad_u64_u32 v[14:15], s[20:21], v14, s81, v[4:5]
	v_mad_u64_u32 v[16:17], s[20:21], v16, s81, v[4:5]
	v_or_b32_e32 v15, s18, v1
	v_or_b32_e32 v17, s19, v0
	v_or_b32_e32 v24, s26, v1
	v_or_b32_e32 v22, s27, v0
	v_or_b32_e32 v28, s28, v1
	v_or_b32_e32 v26, s29, v0
	v_or_b32_e32 v32, s31, v1
	v_or_b32_e32 v30, s35, v0
	v_or_b32_e32 v36, s36, v1
	v_or_b32_e32 v34, s37, v0
	v_or_b32_e32 v40, s38, v1
	v_or_b32_e32 v38, s40, v0
	v_or_b32_e32 v44, s41, v1
	v_or_b32_e32 v42, s42, v0
	s_cmp_lg_u32 s16, 0
	v_mad_u64_u32 v[18:19], s[20:21], v17, s81, v[4:5]
	v_mad_u64_u32 v[20:21], s[20:21], v15, s81, v[4:5]
	v_mad_u64_u32 v[22:23], s[20:21], v22, s81, v[4:5]
	v_mad_u64_u32 v[24:25], s[20:21], v24, s81, v[4:5]
	v_mad_u64_u32 v[26:27], s[20:21], v26, s81, v[4:5]
	v_mad_u64_u32 v[28:29], s[20:21], v28, s81, v[4:5]
	v_mad_u64_u32 v[30:31], s[20:21], v30, s81, v[4:5]
	v_mad_u64_u32 v[32:33], s[20:21], v32, s81, v[4:5]
	v_mad_u64_u32 v[34:35], s[20:21], v34, s81, v[4:5]
	v_mad_u64_u32 v[36:37], s[20:21], v36, s81, v[4:5]
	v_mad_u64_u32 v[38:39], s[20:21], v38, s81, v[4:5]
	v_mad_u64_u32 v[40:41], s[20:21], v40, s81, v[4:5]
	v_mad_u64_u32 v[42:43], s[20:21], v42, s81, v[4:5]
	v_mad_u64_u32 v[44:45], s[20:21], v44, s81, v[4:5]
	s_waitcnt vmcnt(15)
	ds_write_b32 v14, v94
	s_waitcnt vmcnt(14)
	ds_write_b32 v16, v95
	s_waitcnt vmcnt(13)
	ds_write_b32 v18, v96
	s_waitcnt vmcnt(12)
	ds_write_b32 v20, v97
	s_waitcnt vmcnt(11)
	ds_write_b32 v22, v98
	s_waitcnt vmcnt(10)
	ds_write_b32 v24, v99
	s_waitcnt vmcnt(9)
	ds_write_b32 v26, v100
	s_waitcnt vmcnt(8)
	ds_write_b32 v28, v101
	s_waitcnt vmcnt(7)
	ds_write_b32 v30, v102
	s_waitcnt vmcnt(6)
	ds_write_b32 v32, v103
	s_waitcnt vmcnt(5)
	ds_write_b32 v34, v104
	s_waitcnt vmcnt(4)
	ds_write_b32 v36, v105
	s_waitcnt vmcnt(3)
	ds_write_b32 v38, v106
	s_waitcnt vmcnt(2)
	ds_write_b32 v40, v107
	s_waitcnt vmcnt(1)
	ds_write_b32 v42, v108
	s_waitcnt vmcnt(0)
	ds_write_b32 v44, v109
	s_waitcnt lgkmcnt(0)
	ds_read2_b32 v[8:9], v7 offset1:8
	ds_read2_b32 v[20:21], v7 offset0:33 offset1:41
	ds_read2_b32 v[22:23], v7 offset0:66 offset1:74
	s_lshl_b32 s5, s12, 1
	ds_read2_b32 v[24:25], v7 offset0:99 offset1:107
	s_add_u32 s12, s10, s5
	s_waitcnt lgkmcnt(3)
; #define GAS __attribute__((address_space(1)))
; #define LAS __attribute__((address_space(3)))
; #define LDS_WAIT() asm volatile("s_waitcnt lgkmcnt(0)" ::: "memory")
; __device__ __forceinline__ unsigned pk2(float lo, float hi) { return f2bf(lo) | (f2bf(hi) << 16); }
; __device__ __forceinline__ void transpose_item(const float* W, int K, int N, bf16* WT, bool upmap, LAS float* scr, int item, int lane) {
;     ...
;     const int c = lane & 7;
; #pragma unroll
;     for (int j = 0; j < 4; ++j) { const int n = (lane >> 3) + 8 * j; const LAS float* s = scr + (8 * c) * 33 + n;
;         v4u o; o.x = pk2(s[0 * 33], s[1 * 33]); o.y = pk2(s[2 * 33], s[3 * 33]); o.z = pk2(s[4 * 33], s[5 * 33]); o.w = pk2(s[6 * 33], s[7 * 33]);
;         *(GAS v4u*)(WT + (size_t)(d0 + n) * K + k0 + 8 * c) = o; }
;     LDS_WAIT(); asm volatile("" ::: "memory");
	v_bfe_u32 v3, v8, 16, 1
	s_addc_u32 s13, s9, 0
	v_lshlrev_b32_e32 v208, 1, v6
	v_add3_u32 v3, v8, v3, s33
	s_waitcnt lgkmcnt(2)
	v_bfe_u32 v8, v20, 16, 1
	ds_read2_b32 v[26:27], v7 offset0:132 offset1:140
	v_lshl_add_u64 v[14:15], s[12:13], 0, v[208:209]
	s_mov_b64 s[12:13], 0x1000000
	v_lshrrev_b32_e32 v3, 16, v3
	v_add3_u32 v8, v20, v8, s33
	ds_read2_b32 v[28:29], v7 offset0:165 offset1:173
	v_lshl_add_u64 v[18:19], v[14:15], 0, s[12:13]
	v_and_or_b32 v14, v8, s80, v3
	s_waitcnt lgkmcnt(3)
	v_bfe_u32 v3, v22, 16, 1
	v_add3_u32 v3, v22, v3, s33
	s_waitcnt lgkmcnt(2)
	v_bfe_u32 v8, v24, 16, 1
	ds_read2_b32 v[30:31], v7 offset0:198 offset1:206
	v_lshrrev_b32_e32 v3, 16, v3
	v_add3_u32 v8, v24, v8, s33
	ds_read2_b32 v[32:33], v7 offset0:231 offset1:239
	v_and_or_b32 v15, v8, s80, v3
	s_waitcnt lgkmcnt(3)
	v_bfe_u32 v3, v26, 16, 1
	v_add3_u32 v3, v26, v3, s33
	s_waitcnt lgkmcnt(2)
	v_bfe_u32 v8, v28, 16, 1
	v_lshrrev_b32_e32 v3, 16, v3
	v_add3_u32 v8, v28, v8, s33
	v_and_or_b32 v16, v8, s80, v3
	s_waitcnt lgkmcnt(1)
	v_bfe_u32 v3, v30, 16, 1
	v_add3_u32 v3, v30, v3, s33
	s_waitcnt lgkmcnt(0)
	v_bfe_u32 v8, v32, 16, 1
	v_lshrrev_b32_e32 v3, 16, v3
	v_add3_u32 v8, v32, v8, s33
	v_and_or_b32 v17, v8, s80, v3
	v_or_b32_e32 v3, s4, v5
	v_lshlrev_b32_e32 v208, 11, v3
	v_bfe_u32 v3, v9, 16, 1
	v_add3_u32 v3, v9, v3, s33
	v_bfe_u32 v8, v21, 16, 1
	v_lshl_add_u64 v[34:35], v[18:19], 0, v[208:209]
	v_lshrrev_b32_e32 v3, 16, v3
	v_add3_u32 v8, v21, v8, s33
	global_store_dwordx4 v[34:35], v[14:17], off
	v_readlane_b32 s42, v254, 31
	v_readlane_b32 s43, v254, 32
	v_and_or_b32 v14, v8, s80, v3
	v_bfe_u32 v3, v23, 16, 1
	v_add3_u32 v3, v23, v3, s33
	v_bfe_u32 v8, v25, 16, 1
	v_lshrrev_b32_e32 v3, 16, v3
	v_add3_u32 v8, v25, v8, s33
	v_and_or_b32 v15, v8, s80, v3
	v_bfe_u32 v3, v27, 16, 1
	v_add3_u32 v3, v27, v3, s33
	v_bfe_u32 v8, v29, 16, 1
	v_lshrrev_b32_e32 v3, 16, v3
	v_add3_u32 v8, v29, v8, s33
	v_and_or_b32 v16, v8, s80, v3
	v_bfe_u32 v3, v31, 16, 1
	v_add3_u32 v3, v31, v3, s33
	v_bfe_u32 v8, v33, 16, 1
	v_lshrrev_b32_e32 v3, 16, v3
	v_add3_u32 v8, v33, v8, s33
	v_and_or_b32 v17, v8, s80, v3
	v_or_b32_e32 v3, s4, v11
	v_lshlrev_b32_e32 v208, 11, v3
	ds_read2_b32 v[8:9], v7 offset0:16 offset1:24
	v_lshl_add_u64 v[20:21], v[18:19], 0, v[208:209]
	global_store_dwordx4 v[20:21], v[14:17], off
	ds_read2_b32 v[20:21], v7 offset0:49 offset1:57
	ds_read2_b32 v[22:23], v7 offset0:82 offset1:90
	ds_read2_b32 v[24:25], v7 offset0:115 offset1:123
	s_waitcnt lgkmcnt(3)
	v_bfe_u32 v3, v8, 16, 1
	v_add3_u32 v3, v8, v3, s33
	s_waitcnt lgkmcnt(2)
	v_bfe_u32 v8, v20, 16, 1
	ds_read2_b32 v[26:27], v7 offset0:148 offset1:156
	v_lshrrev_b32_e32 v3, 16, v3
	v_add3_u32 v8, v20, v8, s33
	ds_read2_b32 v[28:29], v7 offset0:181 offset1:189
	v_and_or_b32 v14, v8, s80, v3
	s_waitcnt lgkmcnt(3)
	v_bfe_u32 v3, v22, 16, 1
	v_add3_u32 v3, v22, v3, s33
	s_waitcnt lgkmcnt(2)
	v_bfe_u32 v8, v24, 16, 1
	ds_read2_b32 v[30:31], v7 offset0:214 offset1:222
	v_lshrrev_b32_e32 v3, 16, v3
	v_add3_u32 v8, v24, v8, s33
	ds_read2_b32 v[32:33], v7 offset0:247 offset1:255
	v_and_or_b32 v15, v8, s80, v3
	s_waitcnt lgkmcnt(3)
	v_bfe_u32 v3, v26, 16, 1
	v_add3_u32 v3, v26, v3, s33
	s_waitcnt lgkmcnt(2)
	v_bfe_u32 v8, v28, 16, 1
	v_lshrrev_b32_e32 v3, 16, v3
	v_add3_u32 v8, v28, v8, s33
	v_and_or_b32 v16, v8, s80, v3
	s_waitcnt lgkmcnt(1)
	v_bfe_u32 v3, v30, 16, 1
	v_add3_u32 v3, v30, v3, s33
	s_waitcnt lgkmcnt(0)
	v_bfe_u32 v8, v32, 16, 1
	v_lshrrev_b32_e32 v3, 16, v3
	v_add3_u32 v8, v32, v8, s33
	v_and_or_b32 v17, v8, s80, v3
	v_or_b32_e32 v3, s4, v12
	v_lshlrev_b32_e32 v208, 11, v3
	v_bfe_u32 v3, v9, 16, 1
	v_add3_u32 v3, v9, v3, s33
	v_bfe_u32 v8, v21, 16, 1
	v_lshl_add_u64 v[34:35], v[18:19], 0, v[208:209]
	v_lshrrev_b32_e32 v3, 16, v3
	v_add3_u32 v8, v21, v8, s33
	global_store_dwordx4 v[34:35], v[14:17], off
	s_nop 1
	v_and_or_b32 v14, v8, s80, v3
	v_bfe_u32 v3, v23, 16, 1
	v_add3_u32 v3, v23, v3, s33
	v_bfe_u32 v8, v25, 16, 1
	v_lshrrev_b32_e32 v3, 16, v3
	v_add3_u32 v8, v25, v8, s33
	v_and_or_b32 v15, v8, s80, v3
	v_bfe_u32 v3, v27, 16, 1
	v_add3_u32 v3, v27, v3, s33
	v_bfe_u32 v8, v29, 16, 1
	v_lshrrev_b32_e32 v3, 16, v3
	v_add3_u32 v8, v29, v8, s33
	v_and_or_b32 v16, v8, s80, v3
	v_bfe_u32 v3, v31, 16, 1
	v_add3_u32 v3, v31, v3, s33
	v_bfe_u32 v8, v33, 16, 1
	v_lshrrev_b32_e32 v3, 16, v3
	v_add3_u32 v8, v33, v8, s33
	v_and_or_b32 v17, v8, s80, v3
	v_or_b32_e32 v3, s4, v13
	v_lshlrev_b32_e32 v208, 11, v3
	v_lshl_add_u64 v[8:9], v[18:19], 0, v[208:209]
	global_store_dwordx4 v[8:9], v[14:17], off
	s_waitcnt lgkmcnt(0)

; #define LAS __attribute__((address_space(3)))
; #define LDS_WAIT() asm volatile("s_waitcnt lgkmcnt(0)" ::: "memory")
; __device__ __forceinline__ void transpose_item(const float* W, int K, int N, bf16* WT, bool upmap, LAS float* scr, int item, int lane) {
;     const int nblk = N / 32, kb = item / nblk, nb = item % nblk, k0 = 64 * kb, n0 = 32 * nb;
;     int d0 = n0;
;     if (upmap) { const int f = n0 < DFF ? n0 : n0 - DFF; d0 = (f >> 7) * 256 + (f & 127) + (n0 < DFF ? 0 : 128); }
; #pragma unroll 8
;     for (int i = 0; i < 32; ++i) { const int kk = 2 * i + (lane >> 5); scr[kk * 33 + (lane & 31)] = W[(size_t)(k0 + kk) * N + n0 + (lane & 31)]; }
;     LDS_WAIT(); asm volatile("" ::: "memory");
.LBB0_436:
	s_lshl_b32 s20, s5, 1
	s_lshl_b32 s21, s13, 1
	v_or_b32_e32 v208, s21, v10
	s_add_i32 s18, s20, 4
	s_add_i32 s19, s21, 4
	v_mov_b32_e32 v17, v209
	s_add_i32 s27, s21, 8
	v_lshlrev_b64 v[30:31], 12, v[208:209]
	v_or_b32_e32 v16, s18, v3
	v_or_b32_e32 v208, s19, v10
	v_mov_b32_e32 v15, v209
	v_or_b32_e32 v14, s20, v3
	s_add_i32 s29, s21, 12
	v_lshlrev_b64 v[16:17], 12, v[16:17]
	v_lshlrev_b64 v[32:33], 12, v[208:209]
	v_or_b32_e32 v208, s27, v10
	s_add_i32 s26, s20, 8
	s_add_i32 s28, s20, 12
	s_add_i32 s35, s21, 16
	v_lshlrev_b64 v[14:15], 12, v[14:15]
	v_lshl_add_u64 v[30:31], v[8:9], 0, v[30:31]
	v_lshl_add_u64 v[16:17], v[8:9], 0, v[16:17]
	v_lshlrev_b64 v[34:35], 12, v[208:209]
	v_or_b32_e32 v208, s29, v10
	v_mov_b32_e32 v19, v209
	v_mov_b32_e32 v21, v209
	s_add_i32 s37, s21, 20
	v_or_b32_e32 v18, s26, v3
	v_or_b32_e32 v20, s28, v3
	v_lshl_add_u64 v[14:15], v[8:9], 0, v[14:15]
	v_lshl_add_u64 v[32:33], v[8:9], 0, v[32:33]
	global_load_dword v46, v[30:31], off
	global_load_dword v47, v[14:15], off
	global_load_dword v48, v[32:33], off
	global_load_dword v49, v[16:17], off
	v_lshlrev_b64 v[16:17], 12, v[208:209]
	v_or_b32_e32 v208, s35, v10
	s_add_i32 s31, s20, 16
	s_add_i32 s36, s20, 20
	s_add_i32 s40, s21, 24
	v_lshlrev_b64 v[18:19], 12, v[18:19]
	v_lshlrev_b64 v[20:21], 12, v[20:21]
	v_lshl_add_u64 v[14:15], v[8:9], 0, v[34:35]
	v_lshl_add_u64 v[16:17], v[8:9], 0, v[16:17]
	v_lshlrev_b64 v[30:31], 12, v[208:209]
	v_or_b32_e32 v208, s37, v10
	v_mov_b32_e32 v23, v209
	v_mov_b32_e32 v25, v209
	s_add_i32 s38, s20, 24
	s_add_i32 s41, s20, 28
	s_add_i32 s42, s21, 28
	v_or_b32_e32 v22, s31, v3
	v_or_b32_e32 v24, s36, v3
	v_lshl_add_u64 v[18:19], v[8:9], 0, v[18:19]
	v_lshl_add_u64 v[20:21], v[8:9], 0, v[20:21]
	global_load_dword v50, v[14:15], off
	global_load_dword v51, v[18:19], off
	global_load_dword v52, v[16:17], off
	global_load_dword v53, v[20:21], off
	v_lshlrev_b64 v[16:17], 12, v[208:209]
	v_or_b32_e32 v208, s40, v10
	v_mov_b32_e32 v27, v209
	v_mov_b32_e32 v29, v209
	v_or_b32_e32 v26, s38, v3
	v_or_b32_e32 v28, s41, v3
	v_lshlrev_b64 v[22:23], 12, v[22:23]
	v_lshlrev_b64 v[24:25], 12, v[24:25]
	v_lshl_add_u64 v[14:15], v[8:9], 0, v[30:31]
	v_lshl_add_u64 v[16:17], v[8:9], 0, v[16:17]
	v_lshlrev_b64 v[18:19], 12, v[208:209]
	v_or_b32_e32 v208, s42, v10
	v_lshlrev_b64 v[26:27], 12, v[26:27]
	v_lshlrev_b64 v[28:29], 12, v[28:29]
	v_lshl_add_u64 v[22:23], v[8:9], 0, v[22:23]
	v_lshl_add_u64 v[24:25], v[8:9], 0, v[24:25]
	global_load_dword v54, v[14:15], off
	global_load_dword v55, v[22:23], off
	global_load_dword v56, v[16:17], off
	global_load_dword v57, v[24:25], off
	v_lshl_add_u64 v[14:15], v[8:9], 0, v[18:19]
	v_lshlrev_b64 v[16:17], 12, v[208:209]
	v_lshl_add_u64 v[26:27], v[8:9], 0, v[26:27]
	v_lshl_add_u64 v[28:29], v[8:9], 0, v[28:29]
	v_lshl_add_u64 v[16:17], v[8:9], 0, v[16:17]
	global_load_dword v58, v[14:15], off
	global_load_dword v59, v[26:27], off
	global_load_dword v60, v[16:17], off
	global_load_dword v61, v[28:29], off
	v_or_b32_e32 v64, s20, v1
	v_or_b32_e32 v62, s21, v0
	s_add_i32 s13, s13, 16
	s_add_i32 s5, s5, 16
	s_add_i32 s16, s16, -16
	v_mad_u64_u32 v[62:63], s[20:21], v62, s81, v[4:5]
	v_mad_u64_u32 v[64:65], s[20:21], v64, s81, v[4:5]
	v_or_b32_e32 v63, s18, v1
	v_or_b32_e32 v65, s19, v0
	v_or_b32_e32 v72, s26, v1
	v_or_b32_e32 v70, s27, v0
	v_or_b32_e32 v76, s28, v1
	v_or_b32_e32 v74, s29, v0
	v_or_b32_e32 v80, s31, v1
	v_or_b32_e32 v78, s35, v0
	v_or_b32_e32 v84, s36, v1
	v_or_b32_e32 v82, s37, v0
	v_or_b32_e32 v88, s38, v1
	v_or_b32_e32 v86, s40, v0
	v_or_b32_e32 v92, s41, v1
	v_or_b32_e32 v90, s42, v0
	s_cmp_lg_u32 s16, 0
	v_mad_u64_u32 v[66:67], s[20:21], v65, s81, v[4:5]
	v_mad_u64_u32 v[68:69], s[20:21], v63, s81, v[4:5]
	v_mad_u64_u32 v[70:71], s[20:21], v70, s81, v[4:5]
	v_mad_u64_u32 v[72:73], s[20:21], v72, s81, v[4:5]
	v_mad_u64_u32 v[74:75], s[20:21], v74, s81, v[4:5]
	v_mad_u64_u32 v[76:77], s[20:21], v76, s81, v[4:5]
	v_mad_u64_u32 v[78:79], s[20:21], v78, s81, v[4:5]
	v_mad_u64_u32 v[80:81], s[20:21], v80, s81, v[4:5]
	v_mad_u64_u32 v[82:83], s[20:21], v82, s81, v[4:5]
	v_mad_u64_u32 v[84:85], s[20:21], v84, s81, v[4:5]
	v_mad_u64_u32 v[86:87], s[20:21], v86, s81, v[4:5]
	v_mad_u64_u32 v[88:89], s[20:21], v88, s81, v[4:5]
	v_mad_u64_u32 v[90:91], s[20:21], v90, s81, v[4:5]
	v_mad_u64_u32 v[92:93], s[20:21], v92, s81, v[4:5]
	s_lshl_b32 s20, s5, 1
	s_lshl_b32 s21, s13, 1
	v_or_b32_e32 v208, s21, v10
	s_add_i32 s18, s20, 4
	s_add_i32 s19, s21, 4
	v_mov_b32_e32 v17, v209
	s_add_i32 s27, s21, 8
	v_lshlrev_b64 v[30:31], 12, v[208:209]
	v_or_b32_e32 v16, s18, v3
	v_or_b32_e32 v208, s19, v10
	v_mov_b32_e32 v15, v209
	v_or_b32_e32 v14, s20, v3
	s_add_i32 s29, s21, 12
	v_lshlrev_b64 v[16:17], 12, v[16:17]
	v_lshlrev_b64 v[32:33], 12, v[208:209]
	v_or_b32_e32 v208, s27, v10
	s_add_i32 s26, s20, 8
	s_add_i32 s28, s20, 12
	s_add_i32 s35, s21, 16
	v_lshlrev_b64 v[14:15], 12, v[14:15]
	v_lshl_add_u64 v[30:31], v[8:9], 0, v[30:31]
	v_lshl_add_u64 v[16:17], v[8:9], 0, v[16:17]
	v_lshlrev_b64 v[34:35], 12, v[208:209]
	v_or_b32_e32 v208, s29, v10
	v_mov_b32_e32 v19, v209
	v_mov_b32_e32 v21, v209
	s_add_i32 s37, s21, 20
	v_or_b32_e32 v18, s26, v3
	v_or_b32_e32 v20, s28, v3
	v_lshl_add_u64 v[14:15], v[8:9], 0, v[14:15]
	v_lshl_add_u64 v[32:33], v[8:9], 0, v[32:33]
	global_load_dword v94, v[30:31], off
	global_load_dword v95, v[14:15], off
	global_load_dword v96, v[32:33], off
	global_load_dword v97, v[16:17], off
	v_lshlrev_b64 v[16:17], 12, v[208:209]
	v_or_b32_e32 v208, s35, v10
	s_add_i32 s31, s20, 16
	s_add_i32 s36, s20, 20
	s_add_i32 s40, s21, 24
	v_lshlrev_b64 v[18:19], 12, v[18:19]
; #define LDS_WAIT() asm volatile("s_waitcnt lgkmcnt(0)" ::: "memory")
; __device__ __forceinline__ void transpose_item(const float* W, int K, int N, bf16* WT, bool upmap, LAS float* scr, int item, int lane) {
;     ...
; #pragma unroll 8
;     for (int i = 0; i < 32; ++i) { const int kk = 2 * i + (lane >> 5); scr[kk * 33 + (lane & 31)] = W[(size_t)(k0 + kk) * N + n0 + (lane & 31)]; }
;     LDS_WAIT(); asm volatile("" ::: "memory");
	v_lshlrev_b64 v[20:21], 12, v[20:21]
	v_lshl_add_u64 v[14:15], v[8:9], 0, v[34:35]
	v_lshl_add_u64 v[16:17], v[8:9], 0, v[16:17]
	v_lshlrev_b64 v[30:31], 12, v[208:209]
	v_or_b32_e32 v208, s37, v10
	v_mov_b32_e32 v23, v209
	v_mov_b32_e32 v25, v209
	s_add_i32 s38, s20, 24
	s_add_i32 s41, s20, 28
	s_add_i32 s42, s21, 28
	v_or_b32_e32 v22, s31, v3
	v_or_b32_e32 v24, s36, v3
	v_lshl_add_u64 v[18:19], v[8:9], 0, v[18:19]
	v_lshl_add_u64 v[20:21], v[8:9], 0, v[20:21]
	global_load_dword v98, v[14:15], off
	global_load_dword v99, v[18:19], off
	global_load_dword v100, v[16:17], off
	global_load_dword v101, v[20:21], off
	v_lshlrev_b64 v[16:17], 12, v[208:209]
	v_or_b32_e32 v208, s40, v10
	v_mov_b32_e32 v27, v209
	v_mov_b32_e32 v29, v209
	v_or_b32_e32 v26, s38, v3
	v_or_b32_e32 v28, s41, v3
	v_lshlrev_b64 v[22:23], 12, v[22:23]
	v_lshlrev_b64 v[24:25], 12, v[24:25]
	v_lshl_add_u64 v[14:15], v[8:9], 0, v[30:31]
	v_lshl_add_u64 v[16:17], v[8:9], 0, v[16:17]
	v_lshlrev_b64 v[18:19], 12, v[208:209]
	v_or_b32_e32 v208, s42, v10
	v_lshlrev_b64 v[26:27], 12, v[26:27]
	v_lshlrev_b64 v[28:29], 12, v[28:29]
	v_lshl_add_u64 v[22:23], v[8:9], 0, v[22:23]
	v_lshl_add_u64 v[24:25], v[8:9], 0, v[24:25]
	global_load_dword v102, v[14:15], off
	global_load_dword v103, v[22:23], off
	global_load_dword v104, v[16:17], off
	global_load_dword v105, v[24:25], off
	v_lshl_add_u64 v[14:15], v[8:9], 0, v[18:19]
	v_lshlrev_b64 v[16:17], 12, v[208:209]
	v_lshl_add_u64 v[26:27], v[8:9], 0, v[26:27]
	v_lshl_add_u64 v[28:29], v[8:9], 0, v[28:29]
	v_lshl_add_u64 v[16:17], v[8:9], 0, v[16:17]
	global_load_dword v106, v[14:15], off
	global_load_dword v107, v[26:27], off
	global_load_dword v108, v[16:17], off
	global_load_dword v109, v[28:29], off
	s_waitcnt vmcnt(31)
	ds_write_b32 v62, v46
	s_waitcnt vmcnt(30)
	ds_write_b32 v64, v47
	s_waitcnt vmcnt(29)
	ds_write_b32 v66, v48
	s_waitcnt vmcnt(28)
	ds_write_b32 v68, v49
	s_waitcnt vmcnt(27)
	ds_write_b32 v70, v50
	s_waitcnt vmcnt(26)
	ds_write_b32 v72, v51
	s_waitcnt vmcnt(25)
	ds_write_b32 v74, v52
	s_waitcnt vmcnt(24)
	ds_write_b32 v76, v53
	s_waitcnt vmcnt(23)
	ds_write_b32 v78, v54
	s_waitcnt vmcnt(22)
	ds_write_b32 v80, v55
	s_waitcnt vmcnt(21)
	ds_write_b32 v82, v56
	s_waitcnt vmcnt(20)
	ds_write_b32 v84, v57
	s_waitcnt vmcnt(19)
	ds_write_b32 v86, v58
	s_waitcnt vmcnt(18)
	ds_write_b32 v88, v59
	s_waitcnt vmcnt(17)
	ds_write_b32 v90, v60
	s_waitcnt vmcnt(16)
	ds_write_b32 v92, v61
	v_or_b32_e32 v16, s20, v1
	v_or_b32_e32 v14, s21, v0
	s_add_i32 s13, s13, 16
	s_add_i32 s5, s5, 16
	s_add_i32 s16, s16, -16
	v_mad_u64_u32 v[14:15], s[20:21], v14, s81, v[4:5]
	v_mad_u64_u32 v[16:17], s[20:21], v16, s81, v[4:5]
	v_or_b32_e32 v15, s18, v1
	v_or_b32_e32 v17, s19, v0
	v_or_b32_e32 v24, s26, v1
	v_or_b32_e32 v22, s27, v0
	v_or_b32_e32 v28, s28, v1
	v_or_b32_e32 v26, s29, v0
	v_or_b32_e32 v32, s31, v1
	v_or_b32_e32 v30, s35, v0
	v_or_b32_e32 v36, s36, v1
	v_or_b32_e32 v34, s37, v0
	v_or_b32_e32 v40, s38, v1
	v_or_b32_e32 v38, s40, v0
	v_or_b32_e32 v44, s41, v1
	v_or_b32_e32 v42, s42, v0
	s_cmp_lg_u32 s16, 0
	v_mad_u64_u32 v[18:19], s[20:21], v17, s81, v[4:5]
	v_mad_u64_u32 v[20:21], s[20:21], v15, s81, v[4:5]
	v_mad_u64_u32 v[22:23], s[20:21], v22, s81, v[4:5]
	v_mad_u64_u32 v[24:25], s[20:21], v24, s81, v[4:5]
	v_mad_u64_u32 v[26:27], s[20:21], v26, s81, v[4:5]
	v_mad_u64_u32 v[28:29], s[20:21], v28, s81, v[4:5]
	v_mad_u64_u32 v[30:31], s[20:21], v30, s81, v[4:5]
	v_mad_u64_u32 v[32:33], s[20:21], v32, s81, v[4:5]
	v_mad_u64_u32 v[34:35], s[20:21], v34, s81, v[4:5]
	v_mad_u64_u32 v[36:37], s[20:21], v36, s81, v[4:5]
	v_mad_u64_u32 v[38:39], s[20:21], v38, s81, v[4:5]
	v_mad_u64_u32 v[40:41], s[20:21], v40, s81, v[4:5]
	v_mad_u64_u32 v[42:43], s[20:21], v42, s81, v[4:5]
	v_mad_u64_u32 v[44:45], s[20:21], v44, s81, v[4:5]
	s_waitcnt vmcnt(15)
	ds_write_b32 v14, v94
	s_waitcnt vmcnt(14)
	ds_write_b32 v16, v95
	s_waitcnt vmcnt(13)
	ds_write_b32 v18, v96
	s_waitcnt vmcnt(12)
	ds_write_b32 v20, v97
	s_waitcnt vmcnt(11)
	ds_write_b32 v22, v98
	s_waitcnt vmcnt(10)
	ds_write_b32 v24, v99
	s_waitcnt vmcnt(9)
	ds_write_b32 v26, v100
	s_waitcnt vmcnt(8)
	ds_write_b32 v28, v101
	s_waitcnt vmcnt(7)
	ds_write_b32 v30, v102
	s_waitcnt vmcnt(6)
	ds_write_b32 v32, v103
	s_waitcnt vmcnt(5)
	ds_write_b32 v34, v104
	s_waitcnt vmcnt(4)
	ds_write_b32 v36, v105
	s_waitcnt vmcnt(3)
	ds_write_b32 v38, v106
	s_waitcnt vmcnt(2)
	ds_write_b32 v40, v107
	s_waitcnt vmcnt(1)
	ds_write_b32 v42, v108
	s_waitcnt vmcnt(0)
	ds_write_b32 v44, v109
	s_waitcnt lgkmcnt(0)
	ds_read2_b32 v[8:9], v7 offset1:8
	ds_read2_b32 v[20:21], v7 offset0:33 offset1:41
	ds_read2_b32 v[22:23], v7 offset0:66 offset1:74
	s_lshl_b32 s5, s12, 1
	ds_read2_b32 v[24:25], v7 offset0:99 offset1:107
	s_add_u32 s12, s10, s5
	s_waitcnt lgkmcnt(3)
; #define GAS __attribute__((address_space(1)))
; #define LAS __attribute__((address_space(3)))
; #define LDS_WAIT() asm volatile("s_waitcnt lgkmcnt(0)" ::: "memory")
; __device__ __forceinline__ unsigned pk2(float lo, float hi) { return f2bf(lo) | (f2bf(hi) << 16); }
; __device__ __forceinline__ void transpose_item(const float* W, int K, int N, bf16* WT, bool upmap, LAS float* scr, int item, int lane) {
;     ...
;     const int c = lane & 7;
; #pragma unroll
;     for (int j = 0; j < 4; ++j) { const int n = (lane >> 3) + 8 * j; const LAS float* s = scr + (8 * c) * 33 + n;
;         v4u o; o.x = pk2(s[0 * 33], s[1 * 33]); o.y = pk2(s[2 * 33], s[3 * 33]); o.z = pk2(s[4 * 33], s[5 * 33]); o.w = pk2(s[6 * 33], s[7 * 33]);
;         *(GAS v4u*)(WT + (size_t)(d0 + n) * K + k0 + 8 * c) = o; }
;     LDS_WAIT(); asm volatile("" ::: "memory");
	v_bfe_u32 v3, v8, 16, 1
	s_addc_u32 s13, s9, 0
	v_lshlrev_b32_e32 v208, 1, v6
	v_add3_u32 v3, v8, v3, s33
	s_waitcnt lgkmcnt(2)
	v_bfe_u32 v8, v20, 16, 1
	ds_read2_b32 v[26:27], v7 offset0:132 offset1:140
	v_lshl_add_u64 v[14:15], s[12:13], 0, v[208:209]
	s_mov_b64 s[12:13], 0xe00000
	v_lshrrev_b32_e32 v3, 16, v3
	v_add3_u32 v8, v20, v8, s33
	ds_read2_b32 v[28:29], v7 offset0:165 offset1:173
	v_lshl_add_u64 v[18:19], v[14:15], 0, s[12:13]
	v_and_or_b32 v14, v8, s80, v3
	s_waitcnt lgkmcnt(3)
	v_bfe_u32 v3, v22, 16, 1
	v_add3_u32 v3, v22, v3, s33
	s_waitcnt lgkmcnt(2)
	v_bfe_u32 v8, v24, 16, 1
	ds_read2_b32 v[30:31], v7 offset0:198 offset1:206
	v_lshrrev_b32_e32 v3, 16, v3
	v_add3_u32 v8, v24, v8, s33
	ds_read2_b32 v[32:33], v7 offset0:231 offset1:239
	v_and_or_b32 v15, v8, s80, v3
	s_waitcnt lgkmcnt(3)
	v_bfe_u32 v3, v26, 16, 1
	v_add3_u32 v3, v26, v3, s33
	s_waitcnt lgkmcnt(2)
	v_bfe_u32 v8, v28, 16, 1
	v_lshrrev_b32_e32 v3, 16, v3
	v_add3_u32 v8, v28, v8, s33
	v_and_or_b32 v16, v8, s80, v3
	s_waitcnt lgkmcnt(1)
	v_bfe_u32 v3, v30, 16, 1
	v_add3_u32 v3, v30, v3, s33
	s_waitcnt lgkmcnt(0)
	v_bfe_u32 v8, v32, 16, 1
	v_lshrrev_b32_e32 v3, 16, v3
	v_add3_u32 v8, v32, v8, s33
	v_and_or_b32 v17, v8, s80, v3
	v_or_b32_e32 v3, s4, v5
	v_lshlrev_b32_e32 v208, 11, v3
	v_bfe_u32 v3, v9, 16, 1
	v_add3_u32 v3, v9, v3, s33
	v_bfe_u32 v8, v21, 16, 1
	v_lshl_add_u64 v[34:35], v[18:19], 0, v[208:209]
	v_lshrrev_b32_e32 v3, 16, v3
	v_add3_u32 v8, v21, v8, s33
	global_store_dwordx4 v[34:35], v[14:17], off
	v_readlane_b32 s42, v254, 31
	v_readlane_b32 s43, v254, 32
	v_and_or_b32 v14, v8, s80, v3
	v_bfe_u32 v3, v23, 16, 1
	v_add3_u32 v3, v23, v3, s33
	v_bfe_u32 v8, v25, 16, 1
	v_lshrrev_b32_e32 v3, 16, v3
	v_add3_u32 v8, v25, v8, s33
	v_and_or_b32 v15, v8, s80, v3
	v_bfe_u32 v3, v27, 16, 1
	v_add3_u32 v3, v27, v3, s33
	v_bfe_u32 v8, v29, 16, 1
	v_lshrrev_b32_e32 v3, 16, v3
	v_add3_u32 v8, v29, v8, s33
	v_and_or_b32 v16, v8, s80, v3
	v_bfe_u32 v3, v31, 16, 1
	v_add3_u32 v3, v31, v3, s33
	v_bfe_u32 v8, v33, 16, 1
	v_lshrrev_b32_e32 v3, 16, v3
	v_add3_u32 v8, v33, v8, s33
	v_and_or_b32 v17, v8, s80, v3
	v_or_b32_e32 v3, s4, v11
	v_lshlrev_b32_e32 v208, 11, v3
	ds_read2_b32 v[8:9], v7 offset0:16 offset1:24
	v_lshl_add_u64 v[20:21], v[18:19], 0, v[208:209]
	global_store_dwordx4 v[20:21], v[14:17], off
	ds_read2_b32 v[20:21], v7 offset0:49 offset1:57
	ds_read2_b32 v[22:23], v7 offset0:82 offset1:90
	ds_read2_b32 v[24:25], v7 offset0:115 offset1:123
	s_waitcnt lgkmcnt(3)
	v_bfe_u32 v3, v8, 16, 1
	v_add3_u32 v3, v8, v3, s33
	s_waitcnt lgkmcnt(2)
	v_bfe_u32 v8, v20, 16, 1
	ds_read2_b32 v[26:27], v7 offset0:148 offset1:156
	v_lshrrev_b32_e32 v3, 16, v3
	v_add3_u32 v8, v20, v8, s33
	ds_read2_b32 v[28:29], v7 offset0:181 offset1:189
	v_and_or_b32 v14, v8, s80, v3
	s_waitcnt lgkmcnt(3)
	v_bfe_u32 v3, v22, 16, 1
	v_add3_u32 v3, v22, v3, s33
	s_waitcnt lgkmcnt(2)
	v_bfe_u32 v8, v24, 16, 1
	ds_read2_b32 v[30:31], v7 offset0:214 offset1:222
	v_lshrrev_b32_e32 v3, 16, v3
	v_add3_u32 v8, v24, v8, s33
	ds_read2_b32 v[32:33], v7 offset0:247 offset1:255
	v_and_or_b32 v15, v8, s80, v3
	s_waitcnt lgkmcnt(3)
	v_bfe_u32 v3, v26, 16, 1
	v_add3_u32 v3, v26, v3, s33
	s_waitcnt lgkmcnt(2)
	v_bfe_u32 v8, v28, 16, 1
	v_lshrrev_b32_e32 v3, 16, v3
	v_add3_u32 v8, v28, v8, s33
	v_and_or_b32 v16, v8, s80, v3
	s_waitcnt lgkmcnt(1)
	v_bfe_u32 v3, v30, 16, 1
	v_add3_u32 v3, v30, v3, s33
	s_waitcnt lgkmcnt(0)
	v_bfe_u32 v8, v32, 16, 1
	v_lshrrev_b32_e32 v3, 16, v3
	v_add3_u32 v8, v32, v8, s33
	v_and_or_b32 v17, v8, s80, v3
	v_or_b32_e32 v3, s4, v12
	v_lshlrev_b32_e32 v208, 11, v3
	v_bfe_u32 v3, v9, 16, 1
	v_add3_u32 v3, v9, v3, s33
	v_bfe_u32 v8, v21, 16, 1
	v_lshl_add_u64 v[34:35], v[18:19], 0, v[208:209]
	v_lshrrev_b32_e32 v3, 16, v3
	v_add3_u32 v8, v21, v8, s33
	global_store_dwordx4 v[34:35], v[14:17], off
	s_nop 1
	v_and_or_b32 v14, v8, s80, v3
	v_bfe_u32 v3, v23, 16, 1
	v_add3_u32 v3, v23, v3, s33
	v_bfe_u32 v8, v25, 16, 1
	v_lshrrev_b32_e32 v3, 16, v3
	v_add3_u32 v8, v25, v8, s33
	v_and_or_b32 v15, v8, s80, v3
	v_bfe_u32 v3, v27, 16, 1
	v_add3_u32 v3, v27, v3, s33
	v_bfe_u32 v8, v29, 16, 1
	v_lshrrev_b32_e32 v3, 16, v3
	v_add3_u32 v8, v29, v8, s33
	v_and_or_b32 v16, v8, s80, v3
	v_bfe_u32 v3, v31, 16, 1
	v_add3_u32 v3, v31, v3, s33
	v_bfe_u32 v8, v33, 16, 1
	v_lshrrev_b32_e32 v3, 16, v3
	v_add3_u32 v8, v33, v8, s33
	v_and_or_b32 v17, v8, s80, v3
	v_or_b32_e32 v3, s4, v13
	v_lshlrev_b32_e32 v208, 11, v3
	v_lshl_add_u64 v[8:9], v[18:19], 0, v[208:209]
	global_store_dwordx4 v[8:9], v[14:17], off
	s_waitcnt lgkmcnt(0)

; #define LAS __attribute__((address_space(3)))
; #define LDS_WAIT() asm volatile("s_waitcnt lgkmcnt(0)" ::: "memory")
; __device__ __forceinline__ void transpose_item(const float* W, int K, int N, bf16* WT, bool upmap, LAS float* scr, int item, int lane) {
;     const int nblk = N / 32, kb = item / nblk, nb = item % nblk, k0 = 64 * kb, n0 = 32 * nb;
;     int d0 = n0;
;     if (upmap) { const int f = n0 < DFF ? n0 : n0 - DFF; d0 = (f >> 7) * 256 + (f & 127) + (n0 < DFF ? 0 : 128); }
; #pragma unroll 8
;     for (int i = 0; i < 32; ++i) { const int kk = 2 * i + (lane >> 5); scr[kk * 33 + (lane & 31)] = W[(size_t)(k0 + kk) * N + n0 + (lane & 31)]; }
;     LDS_WAIT(); asm volatile("" ::: "memory");
.LBB0_441:
	s_lshl_b32 s16, s5, 1
	s_lshl_b32 s20, s12, 1
	v_or_b32_e32 v208, s20, v10
	s_add_i32 s18, s16, 4
	s_add_i32 s19, s20, 4
	v_mov_b32_e32 v17, v209
	s_add_i32 s27, s20, 8
	v_lshlrev_b64 v[30:31], 13, v[208:209]
	v_or_b32_e32 v16, s18, v3
	v_or_b32_e32 v208, s19, v10
	v_mov_b32_e32 v15, v209
	v_or_b32_e32 v14, s16, v3
	s_add_i32 s29, s20, 12
	v_lshlrev_b64 v[16:17], 13, v[16:17]
	v_lshlrev_b64 v[32:33], 13, v[208:209]
	v_or_b32_e32 v208, s27, v10
	s_add_i32 s26, s16, 8
	s_add_i32 s28, s16, 12
	s_add_i32 s35, s20, 16
	v_lshlrev_b64 v[14:15], 13, v[14:15]
	v_lshl_add_u64 v[30:31], v[8:9], 0, v[30:31]
	v_lshl_add_u64 v[16:17], v[8:9], 0, v[16:17]
	v_lshlrev_b64 v[34:35], 13, v[208:209]
	v_or_b32_e32 v208, s29, v10
	v_mov_b32_e32 v19, v209
	v_mov_b32_e32 v21, v209
	s_add_i32 s37, s20, 20
	v_or_b32_e32 v18, s26, v3
	v_or_b32_e32 v20, s28, v3
	v_lshl_add_u64 v[14:15], v[8:9], 0, v[14:15]
	v_lshl_add_u64 v[32:33], v[8:9], 0, v[32:33]
	global_load_dword v46, v[30:31], off
	global_load_dword v47, v[14:15], off
	global_load_dword v48, v[32:33], off
	global_load_dword v49, v[16:17], off
	v_lshlrev_b64 v[16:17], 13, v[208:209]
	v_or_b32_e32 v208, s35, v10
	s_add_i32 s31, s16, 16
	s_add_i32 s36, s16, 20
	s_add_i32 s40, s20, 24
	v_lshlrev_b64 v[18:19], 13, v[18:19]
	v_lshlrev_b64 v[20:21], 13, v[20:21]
	v_lshl_add_u64 v[14:15], v[8:9], 0, v[34:35]
	v_lshl_add_u64 v[16:17], v[8:9], 0, v[16:17]
	v_lshlrev_b64 v[30:31], 13, v[208:209]
	v_or_b32_e32 v208, s37, v10
	v_mov_b32_e32 v23, v209
	v_mov_b32_e32 v25, v209
	s_add_i32 s38, s16, 24
	s_add_i32 s41, s16, 28
	s_add_i32 s42, s20, 28
	v_or_b32_e32 v22, s31, v3
	v_or_b32_e32 v24, s36, v3
	v_lshl_add_u64 v[18:19], v[8:9], 0, v[18:19]
	v_lshl_add_u64 v[20:21], v[8:9], 0, v[20:21]
	global_load_dword v50, v[14:15], off
	global_load_dword v51, v[18:19], off
	global_load_dword v52, v[16:17], off
	global_load_dword v53, v[20:21], off
	v_lshlrev_b64 v[16:17], 13, v[208:209]
	v_or_b32_e32 v208, s40, v10
	v_mov_b32_e32 v27, v209
	v_mov_b32_e32 v29, v209
	v_or_b32_e32 v26, s38, v3
	v_or_b32_e32 v28, s41, v3
	v_lshlrev_b64 v[22:23], 13, v[22:23]
	v_lshlrev_b64 v[24:25], 13, v[24:25]
	v_lshl_add_u64 v[14:15], v[8:9], 0, v[30:31]
	v_lshl_add_u64 v[16:17], v[8:9], 0, v[16:17]
	v_lshlrev_b64 v[18:19], 13, v[208:209]
	v_or_b32_e32 v208, s42, v10
	v_lshlrev_b64 v[26:27], 13, v[26:27]
	v_lshlrev_b64 v[28:29], 13, v[28:29]
	v_lshl_add_u64 v[22:23], v[8:9], 0, v[22:23]
	v_lshl_add_u64 v[24:25], v[8:9], 0, v[24:25]
	global_load_dword v54, v[14:15], off
	global_load_dword v55, v[22:23], off
	global_load_dword v56, v[16:17], off
	global_load_dword v57, v[24:25], off
	v_lshl_add_u64 v[14:15], v[8:9], 0, v[18:19]
	v_lshlrev_b64 v[16:17], 13, v[208:209]
	v_lshl_add_u64 v[26:27], v[8:9], 0, v[26:27]
	v_lshl_add_u64 v[28:29], v[8:9], 0, v[28:29]
	v_lshl_add_u64 v[16:17], v[8:9], 0, v[16:17]
	global_load_dword v58, v[14:15], off
	global_load_dword v59, v[26:27], off
	global_load_dword v60, v[16:17], off
	global_load_dword v61, v[28:29], off
	v_or_b32_e32 v64, s16, v1
	v_or_b32_e32 v62, s20, v0
	s_add_i32 s12, s12, 16
	s_add_i32 s5, s5, 16
	s_add_i32 s13, s13, -16
	v_mad_u64_u32 v[62:63], s[20:21], v62, s81, v[4:5]
	v_mad_u64_u32 v[64:65], s[20:21], v64, s81, v[4:5]
	v_or_b32_e32 v63, s18, v1
	v_or_b32_e32 v65, s19, v0
	v_or_b32_e32 v72, s26, v1
	v_or_b32_e32 v70, s27, v0
	v_or_b32_e32 v76, s28, v1
	v_or_b32_e32 v74, s29, v0
	v_or_b32_e32 v80, s31, v1
	v_or_b32_e32 v78, s35, v0
	v_or_b32_e32 v84, s36, v1
	v_or_b32_e32 v82, s37, v0
	v_or_b32_e32 v88, s38, v1
	v_or_b32_e32 v86, s40, v0
	v_or_b32_e32 v92, s41, v1
	v_or_b32_e32 v90, s42, v0
	s_cmp_lg_u32 s13, 0
	v_mad_u64_u32 v[66:67], s[20:21], v65, s81, v[4:5]
	v_mad_u64_u32 v[68:69], s[20:21], v63, s81, v[4:5]
	v_mad_u64_u32 v[70:71], s[20:21], v70, s81, v[4:5]
	v_mad_u64_u32 v[72:73], s[20:21], v72, s81, v[4:5]
	v_mad_u64_u32 v[74:75], s[20:21], v74, s81, v[4:5]
	v_mad_u64_u32 v[76:77], s[20:21], v76, s81, v[4:5]
	v_mad_u64_u32 v[78:79], s[20:21], v78, s81, v[4:5]
	v_mad_u64_u32 v[80:81], s[20:21], v80, s81, v[4:5]
	v_mad_u64_u32 v[82:83], s[20:21], v82, s81, v[4:5]
	v_mad_u64_u32 v[84:85], s[20:21], v84, s81, v[4:5]
	v_mad_u64_u32 v[86:87], s[20:21], v86, s81, v[4:5]
	v_mad_u64_u32 v[88:89], s[20:21], v88, s81, v[4:5]
	v_mad_u64_u32 v[90:91], s[20:21], v90, s81, v[4:5]
	v_mad_u64_u32 v[92:93], s[20:21], v92, s81, v[4:5]
	s_lshl_b32 s16, s5, 1
	s_lshl_b32 s20, s12, 1
	v_or_b32_e32 v208, s20, v10
	s_add_i32 s18, s16, 4
	s_add_i32 s19, s20, 4
	v_mov_b32_e32 v17, v209
	s_add_i32 s27, s20, 8
	v_lshlrev_b64 v[30:31], 13, v[208:209]
	v_or_b32_e32 v16, s18, v3
	v_or_b32_e32 v208, s19, v10
	v_mov_b32_e32 v15, v209
	v_or_b32_e32 v14, s16, v3
	s_add_i32 s29, s20, 12
	v_lshlrev_b64 v[16:17], 13, v[16:17]
	v_lshlrev_b64 v[32:33], 13, v[208:209]
	v_or_b32_e32 v208, s27, v10
	s_add_i32 s26, s16, 8
	s_add_i32 s28, s16, 12
	s_add_i32 s35, s20, 16
	v_lshlrev_b64 v[14:15], 13, v[14:15]
	v_lshl_add_u64 v[30:31], v[8:9], 0, v[30:31]
	v_lshl_add_u64 v[16:17], v[8:9], 0, v[16:17]
	v_lshlrev_b64 v[34:35], 13, v[208:209]
	v_or_b32_e32 v208, s29, v10
	v_mov_b32_e32 v19, v209
	v_mov_b32_e32 v21, v209
	s_add_i32 s37, s20, 20
	v_or_b32_e32 v18, s26, v3
	v_or_b32_e32 v20, s28, v3
	v_lshl_add_u64 v[14:15], v[8:9], 0, v[14:15]
	v_lshl_add_u64 v[32:33], v[8:9], 0, v[32:33]
	global_load_dword v94, v[30:31], off
	global_load_dword v95, v[14:15], off
	global_load_dword v96, v[32:33], off
	global_load_dword v97, v[16:17], off
	v_lshlrev_b64 v[16:17], 13, v[208:209]
	v_or_b32_e32 v208, s35, v10
	s_add_i32 s31, s16, 16
	s_add_i32 s36, s16, 20
	s_add_i32 s40, s20, 24
	v_lshlrev_b64 v[18:19], 13, v[18:19]
; #define LDS_WAIT() asm volatile("s_waitcnt lgkmcnt(0)" ::: "memory")
; __device__ __forceinline__ void transpose_item(const float* W, int K, int N, bf16* WT, bool upmap, LAS float* scr, int item, int lane) {
;     ...
; #pragma unroll 8
;     for (int i = 0; i < 32; ++i) { const int kk = 2 * i + (lane >> 5); scr[kk * 33 + (lane & 31)] = W[(size_t)(k0 + kk) * N + n0 + (lane & 31)]; }
;     LDS_WAIT(); asm volatile("" ::: "memory");
	v_lshlrev_b64 v[20:21], 13, v[20:21]
	v_lshl_add_u64 v[14:15], v[8:9], 0, v[34:35]
	v_lshl_add_u64 v[16:17], v[8:9], 0, v[16:17]
	v_lshlrev_b64 v[30:31], 13, v[208:209]
	v_or_b32_e32 v208, s37, v10
	v_mov_b32_e32 v23, v209
	v_mov_b32_e32 v25, v209
	s_add_i32 s38, s16, 24
	s_add_i32 s41, s16, 28
	s_add_i32 s42, s20, 28
	v_or_b32_e32 v22, s31, v3
	v_or_b32_e32 v24, s36, v3
	v_lshl_add_u64 v[18:19], v[8:9], 0, v[18:19]
	v_lshl_add_u64 v[20:21], v[8:9], 0, v[20:21]
	global_load_dword v98, v[14:15], off
	global_load_dword v99, v[18:19], off
	global_load_dword v100, v[16:17], off
	global_load_dword v101, v[20:21], off
	v_lshlrev_b64 v[16:17], 13, v[208:209]
	v_or_b32_e32 v208, s40, v10
	v_mov_b32_e32 v27, v209
	v_mov_b32_e32 v29, v209
	v_or_b32_e32 v26, s38, v3
	v_or_b32_e32 v28, s41, v3
	v_lshlrev_b64 v[22:23], 13, v[22:23]
	v_lshlrev_b64 v[24:25], 13, v[24:25]
	v_lshl_add_u64 v[14:15], v[8:9], 0, v[30:31]
	v_lshl_add_u64 v[16:17], v[8:9], 0, v[16:17]
	v_lshlrev_b64 v[18:19], 13, v[208:209]
	v_or_b32_e32 v208, s42, v10
	v_lshlrev_b64 v[26:27], 13, v[26:27]
	v_lshlrev_b64 v[28:29], 13, v[28:29]
	v_lshl_add_u64 v[22:23], v[8:9], 0, v[22:23]
	v_lshl_add_u64 v[24:25], v[8:9], 0, v[24:25]
	global_load_dword v102, v[14:15], off
	global_load_dword v103, v[22:23], off
	global_load_dword v104, v[16:17], off
	global_load_dword v105, v[24:25], off
	v_lshl_add_u64 v[14:15], v[8:9], 0, v[18:19]
	v_lshlrev_b64 v[16:17], 13, v[208:209]
	v_lshl_add_u64 v[26:27], v[8:9], 0, v[26:27]
	v_lshl_add_u64 v[28:29], v[8:9], 0, v[28:29]
	v_lshl_add_u64 v[16:17], v[8:9], 0, v[16:17]
	global_load_dword v106, v[14:15], off
	global_load_dword v107, v[26:27], off
	global_load_dword v108, v[16:17], off
	global_load_dword v109, v[28:29], off
	s_waitcnt vmcnt(31)
	ds_write_b32 v62, v46
	s_waitcnt vmcnt(30)
	ds_write_b32 v64, v47
	s_waitcnt vmcnt(29)
	ds_write_b32 v66, v48
	s_waitcnt vmcnt(28)
	ds_write_b32 v68, v49
	s_waitcnt vmcnt(27)
	ds_write_b32 v70, v50
	s_waitcnt vmcnt(26)
	ds_write_b32 v72, v51
	s_waitcnt vmcnt(25)
	ds_write_b32 v74, v52
	s_waitcnt vmcnt(24)
	ds_write_b32 v76, v53
	s_waitcnt vmcnt(23)
	ds_write_b32 v78, v54
	s_waitcnt vmcnt(22)
	ds_write_b32 v80, v55
	s_waitcnt vmcnt(21)
	ds_write_b32 v82, v56
	s_waitcnt vmcnt(20)
	ds_write_b32 v84, v57
	s_waitcnt vmcnt(19)
	ds_write_b32 v86, v58
	s_waitcnt vmcnt(18)
	ds_write_b32 v88, v59
	s_waitcnt vmcnt(17)
	ds_write_b32 v90, v60
	s_waitcnt vmcnt(16)
	ds_write_b32 v92, v61
	v_or_b32_e32 v16, s16, v1
	v_or_b32_e32 v14, s20, v0
	s_add_i32 s12, s12, 16
	s_add_i32 s5, s5, 16
	s_add_i32 s13, s13, -16
	v_mad_u64_u32 v[14:15], s[20:21], v14, s81, v[4:5]
	v_mad_u64_u32 v[16:17], s[20:21], v16, s81, v[4:5]
	v_or_b32_e32 v15, s18, v1
	v_or_b32_e32 v17, s19, v0
	v_or_b32_e32 v24, s26, v1
	v_or_b32_e32 v22, s27, v0
	v_or_b32_e32 v28, s28, v1
	v_or_b32_e32 v26, s29, v0
	v_or_b32_e32 v32, s31, v1
	v_or_b32_e32 v30, s35, v0
	v_or_b32_e32 v36, s36, v1
	v_or_b32_e32 v34, s37, v0
	v_or_b32_e32 v40, s38, v1
	v_or_b32_e32 v38, s40, v0
	v_or_b32_e32 v44, s41, v1
	v_or_b32_e32 v42, s42, v0
	s_cmp_lg_u32 s13, 0
	v_mad_u64_u32 v[18:19], s[20:21], v17, s81, v[4:5]
	v_mad_u64_u32 v[20:21], s[20:21], v15, s81, v[4:5]
	v_mad_u64_u32 v[22:23], s[20:21], v22, s81, v[4:5]
	v_mad_u64_u32 v[24:25], s[20:21], v24, s81, v[4:5]
	v_mad_u64_u32 v[26:27], s[20:21], v26, s81, v[4:5]
	v_mad_u64_u32 v[28:29], s[20:21], v28, s81, v[4:5]
	v_mad_u64_u32 v[30:31], s[20:21], v30, s81, v[4:5]
	v_mad_u64_u32 v[32:33], s[20:21], v32, s81, v[4:5]
	v_mad_u64_u32 v[34:35], s[20:21], v34, s81, v[4:5]
	v_mad_u64_u32 v[36:37], s[20:21], v36, s81, v[4:5]
	v_mad_u64_u32 v[38:39], s[20:21], v38, s81, v[4:5]
	v_mad_u64_u32 v[40:41], s[20:21], v40, s81, v[4:5]
	v_mad_u64_u32 v[42:43], s[20:21], v42, s81, v[4:5]
	v_mad_u64_u32 v[44:45], s[20:21], v44, s81, v[4:5]
	s_waitcnt vmcnt(15)
	ds_write_b32 v14, v94
	s_waitcnt vmcnt(14)
	ds_write_b32 v16, v95
	s_waitcnt vmcnt(13)
	ds_write_b32 v18, v96
	s_waitcnt vmcnt(12)
	ds_write_b32 v20, v97
	s_waitcnt vmcnt(11)
	ds_write_b32 v22, v98
	s_waitcnt vmcnt(10)
	ds_write_b32 v24, v99
	s_waitcnt vmcnt(9)
	ds_write_b32 v26, v100
	s_waitcnt vmcnt(8)
	ds_write_b32 v28, v101
	s_waitcnt vmcnt(7)
	ds_write_b32 v30, v102
	s_waitcnt vmcnt(6)
	ds_write_b32 v32, v103
	s_waitcnt vmcnt(5)
	ds_write_b32 v34, v104
	s_waitcnt vmcnt(4)
	ds_write_b32 v36, v105
	s_waitcnt vmcnt(3)
	ds_write_b32 v38, v106
	s_waitcnt vmcnt(2)
	ds_write_b32 v40, v107
	s_waitcnt vmcnt(1)
	ds_write_b32 v42, v108
	s_waitcnt vmcnt(0)
	ds_write_b32 v44, v109
	s_waitcnt lgkmcnt(0)
	ds_read2_b32 v[8:9], v7 offset1:8
	ds_read2_b32 v[20:21], v7 offset0:33 offset1:41
	ds_read2_b32 v[22:23], v7 offset0:66 offset1:74
	s_lshl_b32 s4, s4, 1
	ds_read2_b32 v[24:25], v7 offset0:99 offset1:107
	s_add_u32 s4, s10, s4
	s_waitcnt lgkmcnt(3)
; #define GAS __attribute__((address_space(1)))
; #define LAS __attribute__((address_space(3)))
; #define LDS_WAIT() asm volatile("s_waitcnt lgkmcnt(0)" ::: "memory")
; __device__ __forceinline__ unsigned pk2(float lo, float hi) { return f2bf(lo) | (f2bf(hi) << 16); }
; __device__ __forceinline__ void transpose_item(const float* W, int K, int N, bf16* WT, bool upmap, LAS float* scr, int item, int lane) {
;     ...
;     const int c = lane & 7;
; #pragma unroll
;     for (int j = 0; j < 4; ++j) { const int n = (lane >> 3) + 8 * j; const LAS float* s = scr + (8 * c) * 33 + n;
;         v4u o; o.x = pk2(s[0 * 33], s[1 * 33]); o.y = pk2(s[2 * 33], s[3 * 33]); o.z = pk2(s[4 * 33], s[5 * 33]); o.w = pk2(s[6 * 33], s[7 * 33]);
;         *(GAS v4u*)(WT + (size_t)(d0 + n) * K + k0 + 8 * c) = o; }
;     LDS_WAIT(); asm volatile("" ::: "memory");
	v_bfe_u32 v3, v8, 16, 1
	s_addc_u32 s5, s9, 0
	v_lshlrev_b32_e32 v208, 1, v6
	v_add3_u32 v3, v8, v3, s33
	s_waitcnt lgkmcnt(2)
	v_bfe_u32 v8, v20, 16, 1
	ds_read2_b32 v[26:27], v7 offset0:132 offset1:140
	v_lshl_add_u64 v[14:15], s[4:5], 0, v[208:209]
	s_mov_b64 s[4:5], 0xa00000
	v_lshrrev_b32_e32 v3, 16, v3
	v_add3_u32 v8, v20, v8, s33
	ds_read2_b32 v[28:29], v7 offset0:165 offset1:173
	v_lshl_add_u64 v[18:19], v[14:15], 0, s[4:5]
	v_and_or_b32 v14, v8, s80, v3
	s_waitcnt lgkmcnt(3)
	v_bfe_u32 v3, v22, 16, 1
	v_add3_u32 v3, v22, v3, s33
	s_waitcnt lgkmcnt(2)
	v_bfe_u32 v8, v24, 16, 1
	ds_read2_b32 v[30:31], v7 offset0:198 offset1:206
	v_lshrrev_b32_e32 v3, 16, v3
	v_add3_u32 v8, v24, v8, s33
	ds_read2_b32 v[32:33], v7 offset0:231 offset1:239
	v_and_or_b32 v15, v8, s80, v3
	s_waitcnt lgkmcnt(3)
	v_bfe_u32 v3, v26, 16, 1
	v_add3_u32 v3, v26, v3, s33
	s_waitcnt lgkmcnt(2)
	v_bfe_u32 v8, v28, 16, 1
	v_lshrrev_b32_e32 v3, 16, v3
	v_add3_u32 v8, v28, v8, s33
	v_and_or_b32 v16, v8, s80, v3
	s_waitcnt lgkmcnt(1)
	v_bfe_u32 v3, v30, 16, 1
	v_add3_u32 v3, v30, v3, s33
	s_waitcnt lgkmcnt(0)
	v_bfe_u32 v8, v32, 16, 1
	v_lshrrev_b32_e32 v3, 16, v3
	v_add3_u32 v8, v32, v8, s33
	v_and_or_b32 v17, v8, s80, v3
	v_or_b32_e32 v3, s3, v5
	v_lshlrev_b32_e32 v208, 11, v3
	v_bfe_u32 v3, v9, 16, 1
	v_add3_u32 v3, v9, v3, s33
	v_bfe_u32 v8, v21, 16, 1
	v_lshl_add_u64 v[34:35], v[18:19], 0, v[208:209]
	v_lshrrev_b32_e32 v3, 16, v3
	v_add3_u32 v8, v21, v8, s33
	global_store_dwordx4 v[34:35], v[14:17], off
	v_readlane_b32 s42, v254, 31
	v_readlane_b32 s43, v254, 32
	v_and_or_b32 v14, v8, s80, v3
	v_bfe_u32 v3, v23, 16, 1
	v_add3_u32 v3, v23, v3, s33
	v_bfe_u32 v8, v25, 16, 1
	v_lshrrev_b32_e32 v3, 16, v3
	v_add3_u32 v8, v25, v8, s33
	v_and_or_b32 v15, v8, s80, v3
	v_bfe_u32 v3, v27, 16, 1
	v_add3_u32 v3, v27, v3, s33
	v_bfe_u32 v8, v29, 16, 1
	v_lshrrev_b32_e32 v3, 16, v3
	v_add3_u32 v8, v29, v8, s33
	v_and_or_b32 v16, v8, s80, v3
	v_bfe_u32 v3, v31, 16, 1
	v_add3_u32 v3, v31, v3, s33
	v_bfe_u32 v8, v33, 16, 1
	v_lshrrev_b32_e32 v3, 16, v3
	v_add3_u32 v8, v33, v8, s33
	v_and_or_b32 v17, v8, s80, v3
	v_or_b32_e32 v3, s3, v11
	v_lshlrev_b32_e32 v208, 11, v3
	ds_read2_b32 v[8:9], v7 offset0:16 offset1:24
	v_lshl_add_u64 v[20:21], v[18:19], 0, v[208:209]
	global_store_dwordx4 v[20:21], v[14:17], off
	ds_read2_b32 v[20:21], v7 offset0:49 offset1:57
	ds_read2_b32 v[22:23], v7 offset0:82 offset1:90
	ds_read2_b32 v[24:25], v7 offset0:115 offset1:123
	s_waitcnt lgkmcnt(3)
	v_bfe_u32 v3, v8, 16, 1
	v_add3_u32 v3, v8, v3, s33
	s_waitcnt lgkmcnt(2)
	v_bfe_u32 v8, v20, 16, 1
	ds_read2_b32 v[26:27], v7 offset0:148 offset1:156
	v_lshrrev_b32_e32 v3, 16, v3
	v_add3_u32 v8, v20, v8, s33
	ds_read2_b32 v[28:29], v7 offset0:181 offset1:189
	v_and_or_b32 v14, v8, s80, v3
	s_waitcnt lgkmcnt(3)
	v_bfe_u32 v3, v22, 16, 1
	v_add3_u32 v3, v22, v3, s33
	s_waitcnt lgkmcnt(2)
	v_bfe_u32 v8, v24, 16, 1
	ds_read2_b32 v[30:31], v7 offset0:214 offset1:222
	v_lshrrev_b32_e32 v3, 16, v3
	v_add3_u32 v8, v24, v8, s33
	ds_read2_b32 v[32:33], v7 offset0:247 offset1:255
	v_and_or_b32 v15, v8, s80, v3
	s_waitcnt lgkmcnt(3)
	v_bfe_u32 v3, v26, 16, 1
	v_add3_u32 v3, v26, v3, s33
	s_waitcnt lgkmcnt(2)
	v_bfe_u32 v8, v28, 16, 1
	v_lshrrev_b32_e32 v3, 16, v3
	v_add3_u32 v8, v28, v8, s33
	v_and_or_b32 v16, v8, s80, v3
	s_waitcnt lgkmcnt(1)
	v_bfe_u32 v3, v30, 16, 1
	v_add3_u32 v3, v30, v3, s33
	s_waitcnt lgkmcnt(0)
	v_bfe_u32 v8, v32, 16, 1
	v_lshrrev_b32_e32 v3, 16, v3
	v_add3_u32 v8, v32, v8, s33
	v_and_or_b32 v17, v8, s80, v3
	v_or_b32_e32 v3, s3, v12
	v_lshlrev_b32_e32 v208, 11, v3
	v_bfe_u32 v3, v9, 16, 1
	v_add3_u32 v3, v9, v3, s33
	v_bfe_u32 v8, v21, 16, 1
	v_lshl_add_u64 v[34:35], v[18:19], 0, v[208:209]
	v_lshrrev_b32_e32 v3, 16, v3
	v_add3_u32 v8, v21, v8, s33
	global_store_dwordx4 v[34:35], v[14:17], off
	s_nop 1
	v_and_or_b32 v14, v8, s80, v3
	v_bfe_u32 v3, v23, 16, 1
	v_add3_u32 v3, v23, v3, s33
	v_bfe_u32 v8, v25, 16, 1
	v_lshrrev_b32_e32 v3, 16, v3
	v_add3_u32 v8, v25, v8, s33
	v_and_or_b32 v15, v8, s80, v3
	v_bfe_u32 v3, v27, 16, 1
	v_add3_u32 v3, v27, v3, s33
	v_bfe_u32 v8, v29, 16, 1
	v_lshrrev_b32_e32 v3, 16, v3
	v_add3_u32 v8, v29, v8, s33
	v_and_or_b32 v16, v8, s80, v3
	v_bfe_u32 v3, v31, 16, 1
	v_add3_u32 v3, v31, v3, s33
	v_bfe_u32 v8, v33, 16, 1
	v_lshrrev_b32_e32 v3, 16, v3
	v_add3_u32 v8, v33, v8, s33
	v_and_or_b32 v17, v8, s80, v3
	v_or_b32_e32 v3, s3, v13
	v_lshlrev_b32_e32 v208, 11, v3
	v_lshl_add_u64 v[8:9], v[18:19], 0, v[208:209]
	global_store_dwordx4 v[8:9], v[14:17], off
	s_waitcnt lgkmcnt(0)

; #define LAS __attribute__((address_space(3)))
; #define LDS_WAIT() asm volatile("s_waitcnt lgkmcnt(0)" ::: "memory")
; __device__ __forceinline__ void transpose_item(const float* W, int K, int N, bf16* WT, bool upmap, LAS float* scr, int item, int lane) {
;     const int nblk = N / 32, kb = item / nblk, nb = item % nblk, k0 = 64 * kb, n0 = 32 * nb;
;     int d0 = n0;
;     if (upmap) { const int f = n0 < DFF ? n0 : n0 - DFF; d0 = (f >> 7) * 256 + (f & 127) + (n0 < DFF ? 0 : 128); }
; #pragma unroll 8
;     for (int i = 0; i < 32; ++i) { const int kk = 2 * i + (lane >> 5); scr[kk * 33 + (lane & 31)] = W[(size_t)(k0 + kk) * N + n0 + (lane & 31)]; }
;     LDS_WAIT(); asm volatile("" ::: "memory");
.LBB0_445:
	s_lshl_b32 s16, s3, 1
	s_lshl_b32 s18, s5, 1
	v_or_b32_e32 v14, s18, v10
	s_add_i32 s19, s16, 4
	s_add_i32 s20, s18, 4
	s_add_i32 s21, s16, 8
	s_add_i32 s26, s18, 8
	s_add_i32 s27, s16, 12
	s_add_i32 s28, s18, 12
	s_add_i32 s29, s16, 16
	s_add_i32 s31, s18, 16
	s_add_i32 s35, s16, 20
	s_add_i32 s36, s18, 20
	s_add_i32 s37, s16, 24
	s_add_i32 s38, s18, 24
	s_add_i32 s40, s16, 28
	s_add_i32 s41, s18, 28
	v_or_b32_e32 v16, s16, v3
	v_mad_i64_i32 v[14:15], s[12:13], v14, s88, v[8:9]
	v_or_b32_e32 v20, s19, v3
	v_or_b32_e32 v18, s20, v10
	v_or_b32_e32 v24, s21, v3
	v_or_b32_e32 v22, s26, v10
	v_or_b32_e32 v28, s27, v3
	v_or_b32_e32 v26, s28, v10
	v_or_b32_e32 v32, s29, v3
	v_or_b32_e32 v30, s31, v10
	v_or_b32_e32 v36, s35, v3
	v_or_b32_e32 v34, s36, v10
	v_or_b32_e32 v40, s37, v3
	v_or_b32_e32 v38, s38, v10
	v_or_b32_e32 v44, s40, v3
	v_or_b32_e32 v42, s41, v10
	v_mad_i64_i32 v[16:17], s[12:13], v16, s88, v[8:9]
	v_mad_i64_i32 v[18:19], s[12:13], v18, s88, v[8:9]
	v_mad_i64_i32 v[20:21], s[12:13], v20, s88, v[8:9]
	v_mad_i64_i32 v[22:23], s[12:13], v22, s88, v[8:9]
	v_mad_i64_i32 v[24:25], s[12:13], v24, s88, v[8:9]
	v_mad_i64_i32 v[26:27], s[12:13], v26, s88, v[8:9]
	v_mad_i64_i32 v[28:29], s[12:13], v28, s88, v[8:9]
	v_mad_i64_i32 v[30:31], s[12:13], v30, s88, v[8:9]
	v_mad_i64_i32 v[32:33], s[12:13], v32, s88, v[8:9]
	v_mad_i64_i32 v[34:35], s[12:13], v34, s88, v[8:9]
	v_mad_i64_i32 v[36:37], s[12:13], v36, s88, v[8:9]
	v_mad_i64_i32 v[38:39], s[12:13], v38, s88, v[8:9]
	v_mad_i64_i32 v[40:41], s[12:13], v40, s88, v[8:9]
	v_mad_i64_i32 v[42:43], s[12:13], v42, s88, v[8:9]
	v_mad_i64_i32 v[44:45], s[12:13], v44, s88, v[8:9]
	global_load_dword v46, v[14:15], off
	global_load_dword v47, v[16:17], off
	global_load_dword v48, v[18:19], off
	global_load_dword v49, v[20:21], off
	global_load_dword v50, v[22:23], off
	global_load_dword v51, v[24:25], off
	global_load_dword v52, v[26:27], off
	global_load_dword v53, v[28:29], off
	global_load_dword v54, v[30:31], off
	global_load_dword v55, v[32:33], off
	global_load_dword v56, v[34:35], off
	global_load_dword v57, v[36:37], off
	global_load_dword v58, v[38:39], off
	global_load_dword v59, v[40:41], off
	global_load_dword v60, v[42:43], off
	global_load_dword v61, v[44:45], off
	v_or_b32_e32 v64, s16, v1
	v_or_b32_e32 v62, s18, v0
	s_add_i32 s5, s5, 16
	s_add_i32 s3, s3, 16
	s_add_i32 s11, s11, -16
	v_mad_u64_u32 v[62:63], s[12:13], v62, s81, v[4:5]
	v_mad_u64_u32 v[64:65], s[12:13], v64, s81, v[4:5]
	v_or_b32_e32 v63, s19, v1
	v_or_b32_e32 v65, s20, v0
	v_or_b32_e32 v72, s21, v1
	v_or_b32_e32 v70, s26, v0
	v_or_b32_e32 v76, s27, v1
	v_or_b32_e32 v74, s28, v0
	v_or_b32_e32 v80, s29, v1
	v_or_b32_e32 v78, s31, v0
	v_or_b32_e32 v84, s35, v1
	v_or_b32_e32 v82, s36, v0
	v_or_b32_e32 v88, s37, v1
	v_or_b32_e32 v86, s38, v0
	v_or_b32_e32 v92, s40, v1
	v_or_b32_e32 v90, s41, v0
	s_cmp_lg_u32 s11, 0
	v_mad_u64_u32 v[66:67], s[12:13], v65, s81, v[4:5]
	v_mad_u64_u32 v[68:69], s[12:13], v63, s81, v[4:5]
	v_mad_u64_u32 v[70:71], s[12:13], v70, s81, v[4:5]
	v_mad_u64_u32 v[72:73], s[12:13], v72, s81, v[4:5]
	v_mad_u64_u32 v[74:75], s[12:13], v74, s81, v[4:5]
	v_mad_u64_u32 v[76:77], s[12:13], v76, s81, v[4:5]
	v_mad_u64_u32 v[78:79], s[12:13], v78, s81, v[4:5]
	v_mad_u64_u32 v[80:81], s[12:13], v80, s81, v[4:5]
	v_mad_u64_u32 v[82:83], s[12:13], v82, s81, v[4:5]
	v_mad_u64_u32 v[84:85], s[12:13], v84, s81, v[4:5]
	v_mad_u64_u32 v[86:87], s[12:13], v86, s81, v[4:5]
	v_mad_u64_u32 v[88:89], s[12:13], v88, s81, v[4:5]
	v_mad_u64_u32 v[90:91], s[12:13], v90, s81, v[4:5]
	v_mad_u64_u32 v[92:93], s[12:13], v92, s81, v[4:5]
	s_lshl_b32 s16, s3, 1
	s_lshl_b32 s18, s5, 1
	v_or_b32_e32 v14, s18, v10
	s_add_i32 s19, s16, 4
	s_add_i32 s20, s18, 4
	s_add_i32 s21, s16, 8
	s_add_i32 s26, s18, 8
	s_add_i32 s27, s16, 12
	s_add_i32 s28, s18, 12
	s_add_i32 s29, s16, 16
	s_add_i32 s31, s18, 16
	s_add_i32 s35, s16, 20
	s_add_i32 s36, s18, 20
	s_add_i32 s37, s16, 24
	s_add_i32 s38, s18, 24
	s_add_i32 s40, s16, 28
	s_add_i32 s41, s18, 28
	v_or_b32_e32 v16, s16, v3
	v_mad_i64_i32 v[14:15], s[12:13], v14, s88, v[8:9]
	v_or_b32_e32 v20, s19, v3
	v_or_b32_e32 v18, s20, v10
	v_or_b32_e32 v24, s21, v3
	v_or_b32_e32 v22, s26, v10
	v_or_b32_e32 v28, s27, v3
	v_or_b32_e32 v26, s28, v10
	v_or_b32_e32 v32, s29, v3
	v_or_b32_e32 v30, s31, v10
	v_or_b32_e32 v36, s35, v3
	v_or_b32_e32 v34, s36, v10
	v_or_b32_e32 v40, s37, v3
	v_or_b32_e32 v38, s38, v10
	v_or_b32_e32 v44, s40, v3
	v_or_b32_e32 v42, s41, v10
	v_mad_i64_i32 v[16:17], s[12:13], v16, s88, v[8:9]
	v_mad_i64_i32 v[18:19], s[12:13], v18, s88, v[8:9]
	v_mad_i64_i32 v[20:21], s[12:13], v20, s88, v[8:9]
	v_mad_i64_i32 v[22:23], s[12:13], v22, s88, v[8:9]
	v_mad_i64_i32 v[24:25], s[12:13], v24, s88, v[8:9]
	v_mad_i64_i32 v[26:27], s[12:13], v26, s88, v[8:9]
	v_mad_i64_i32 v[28:29], s[12:13], v28, s88, v[8:9]
	v_mad_i64_i32 v[30:31], s[12:13], v30, s88, v[8:9]
	v_mad_i64_i32 v[32:33], s[12:13], v32, s88, v[8:9]
	v_mad_i64_i32 v[34:35], s[12:13], v34, s88, v[8:9]
	v_mad_i64_i32 v[36:37], s[12:13], v36, s88, v[8:9]
	v_mad_i64_i32 v[38:39], s[12:13], v38, s88, v[8:9]
	v_mad_i64_i32 v[40:41], s[12:13], v40, s88, v[8:9]
	v_mad_i64_i32 v[42:43], s[12:13], v42, s88, v[8:9]
	v_mad_i64_i32 v[44:45], s[12:13], v44, s88, v[8:9]
	global_load_dword v94, v[14:15], off
	global_load_dword v95, v[16:17], off
	global_load_dword v96, v[18:19], off
	global_load_dword v97, v[20:21], off
	global_load_dword v98, v[22:23], off
	global_load_dword v99, v[24:25], off
	global_load_dword v100, v[26:27], off
	global_load_dword v101, v[28:29], off
	global_load_dword v102, v[30:31], off
	global_load_dword v103, v[32:33], off
	global_load_dword v104, v[34:35], off
	global_load_dword v105, v[36:37], off
	global_load_dword v106, v[38:39], off
	global_load_dword v107, v[40:41], off
	global_load_dword v108, v[42:43], off
	global_load_dword v109, v[44:45], off
	s_waitcnt vmcnt(31)
; #define GAS __attribute__((address_space(1)))
; #define LAS __attribute__((address_space(3)))
; #define LDS_WAIT() asm volatile("s_waitcnt lgkmcnt(0)" ::: "memory")
; __device__ __forceinline__ unsigned pk2(float lo, float hi) { return f2bf(lo) | (f2bf(hi) << 16); }
; __device__ __forceinline__ void transpose_item(const float* W, int K, int N, bf16* WT, bool upmap, LAS float* scr, int item, int lane) {
;     ...
; #pragma unroll 8
;     for (int i = 0; i < 32; ++i) { const int kk = 2 * i + (lane >> 5); scr[kk * 33 + (lane & 31)] = W[(size_t)(k0 + kk) * N + n0 + (lane & 31)]; }
;     LDS_WAIT(); asm volatile("" ::: "memory");
;     const int c = lane & 7;
; #pragma unroll
;     for (int j = 0; j < 4; ++j) { const int n = (lane >> 3) + 8 * j; const LAS float* s = scr + (8 * c) * 33 + n;
;         v4u o; o.x = pk2(s[0 * 33], s[1 * 33]); o.y = pk2(s[2 * 33], s[3 * 33]); o.z = pk2(s[4 * 33], s[5 * 33]); o.w = pk2(s[6 * 33], s[7 * 33]);
;         *(GAS v4u*)(WT + (size_t)(d0 + n) * K + k0 + 8 * c) = o; }
;     LDS_WAIT(); asm volatile("" ::: "memory");
	ds_write_b32 v62, v46
	s_waitcnt vmcnt(30)
	ds_write_b32 v64, v47
	s_waitcnt vmcnt(29)
	ds_write_b32 v66, v48
	s_waitcnt vmcnt(28)
	ds_write_b32 v68, v49
	s_waitcnt vmcnt(27)
	ds_write_b32 v70, v50
	s_waitcnt vmcnt(26)
	ds_write_b32 v72, v51
	s_waitcnt vmcnt(25)
	ds_write_b32 v74, v52
	s_waitcnt vmcnt(24)
	ds_write_b32 v76, v53
	s_waitcnt vmcnt(23)
	ds_write_b32 v78, v54
	s_waitcnt vmcnt(22)
	ds_write_b32 v80, v55
	s_waitcnt vmcnt(21)
	ds_write_b32 v82, v56
	s_waitcnt vmcnt(20)
	ds_write_b32 v84, v57
	s_waitcnt vmcnt(19)
	ds_write_b32 v86, v58
	s_waitcnt vmcnt(18)
	ds_write_b32 v88, v59
	s_waitcnt vmcnt(17)
	ds_write_b32 v90, v60
	s_waitcnt vmcnt(16)
	ds_write_b32 v92, v61
	v_or_b32_e32 v16, s16, v1
	v_or_b32_e32 v14, s18, v0
	s_add_i32 s5, s5, 16
	s_add_i32 s3, s3, 16
	s_add_i32 s11, s11, -16
	v_mad_u64_u32 v[14:15], s[12:13], v14, s81, v[4:5]
	v_mad_u64_u32 v[16:17], s[12:13], v16, s81, v[4:5]
	v_or_b32_e32 v15, s19, v1
	v_or_b32_e32 v17, s20, v0
	v_or_b32_e32 v24, s21, v1
	v_or_b32_e32 v22, s26, v0
	v_or_b32_e32 v28, s27, v1
	v_or_b32_e32 v26, s28, v0
	v_or_b32_e32 v32, s29, v1
	v_or_b32_e32 v30, s31, v0
	v_or_b32_e32 v36, s35, v1
	v_or_b32_e32 v34, s36, v0
	v_or_b32_e32 v40, s37, v1
	v_or_b32_e32 v38, s38, v0
	v_or_b32_e32 v44, s40, v1
	v_or_b32_e32 v42, s41, v0
	s_cmp_lg_u32 s11, 0
	v_mad_u64_u32 v[18:19], s[12:13], v17, s81, v[4:5]
	v_mad_u64_u32 v[20:21], s[12:13], v15, s81, v[4:5]
	v_mad_u64_u32 v[22:23], s[12:13], v22, s81, v[4:5]
	v_mad_u64_u32 v[24:25], s[12:13], v24, s81, v[4:5]
	v_mad_u64_u32 v[26:27], s[12:13], v26, s81, v[4:5]
	v_mad_u64_u32 v[28:29], s[12:13], v28, s81, v[4:5]
	v_mad_u64_u32 v[30:31], s[12:13], v30, s81, v[4:5]
	v_mad_u64_u32 v[32:33], s[12:13], v32, s81, v[4:5]
	v_mad_u64_u32 v[34:35], s[12:13], v34, s81, v[4:5]
	v_mad_u64_u32 v[36:37], s[12:13], v36, s81, v[4:5]
	v_mad_u64_u32 v[38:39], s[12:13], v38, s81, v[4:5]
	v_mad_u64_u32 v[40:41], s[12:13], v40, s81, v[4:5]
	v_mad_u64_u32 v[42:43], s[12:13], v42, s81, v[4:5]
	v_mad_u64_u32 v[44:45], s[12:13], v44, s81, v[4:5]
	s_waitcnt vmcnt(15)
	ds_write_b32 v14, v94
	s_waitcnt vmcnt(14)
	ds_write_b32 v16, v95
	s_waitcnt vmcnt(13)
	ds_write_b32 v18, v96
	s_waitcnt vmcnt(12)
	ds_write_b32 v20, v97
	s_waitcnt vmcnt(11)
	ds_write_b32 v22, v98
	s_waitcnt vmcnt(10)
	ds_write_b32 v24, v99
	s_waitcnt vmcnt(9)
	ds_write_b32 v26, v100
	s_waitcnt vmcnt(8)
	ds_write_b32 v28, v101
	s_waitcnt vmcnt(7)
	ds_write_b32 v30, v102
	s_waitcnt vmcnt(6)
	ds_write_b32 v32, v103
	s_waitcnt vmcnt(5)
	ds_write_b32 v34, v104
	s_waitcnt vmcnt(4)
	ds_write_b32 v36, v105
	s_waitcnt vmcnt(3)
	ds_write_b32 v38, v106
	s_waitcnt vmcnt(2)
	ds_write_b32 v40, v107
	s_waitcnt vmcnt(1)
	ds_write_b32 v42, v108
	s_waitcnt vmcnt(0)
	ds_write_b32 v44, v109
	s_waitcnt lgkmcnt(0)
	ds_read2_b32 v[8:9], v7 offset1:8
	ds_read2_b32 v[20:21], v7 offset0:33 offset1:41
	ds_read2_b32 v[22:23], v7 offset0:66 offset1:74
	ds_read2_b32 v[24:25], v7 offset0:99 offset1:107
	ds_read2_b32 v[26:27], v7 offset0:132 offset1:140
	s_waitcnt lgkmcnt(4)
	v_bfe_u32 v3, v8, 16, 1
	v_add3_u32 v3, v8, v3, s33
	s_waitcnt lgkmcnt(3)
	v_bfe_u32 v8, v20, 16, 1
	v_lshrrev_b32_e32 v3, 16, v3
	v_add3_u32 v8, v20, v8, s33
	ds_read2_b32 v[28:29], v7 offset0:165 offset1:173
	v_and_or_b32 v14, v8, s80, v3
	s_waitcnt lgkmcnt(3)
	v_bfe_u32 v3, v22, 16, 1
	v_add3_u32 v3, v22, v3, s33
	s_waitcnt lgkmcnt(2)
	v_bfe_u32 v8, v24, 16, 1
	ds_read2_b32 v[30:31], v7 offset0:198 offset1:206
	v_lshrrev_b32_e32 v3, 16, v3
	v_add3_u32 v8, v24, v8, s33
	ds_read2_b32 v[32:33], v7 offset0:231 offset1:239
	v_and_or_b32 v15, v8, s80, v3
	s_waitcnt lgkmcnt(3)
	v_bfe_u32 v3, v26, 16, 1
	v_add3_u32 v3, v26, v3, s33
	s_waitcnt lgkmcnt(2)
	v_bfe_u32 v8, v28, 16, 1
	v_lshrrev_b32_e32 v3, 16, v3
	v_add3_u32 v8, v28, v8, s33
	s_ashr_i32 s5, s4, 31
	v_and_or_b32 v16, v8, s80, v3
	s_waitcnt lgkmcnt(1)
; #define GAS __attribute__((address_space(1)))
; #define LAS __attribute__((address_space(3)))
; #define LDS_WAIT() asm volatile("s_waitcnt lgkmcnt(0)" ::: "memory")
; __device__ __forceinline__ unsigned pk2(float lo, float hi) { return f2bf(lo) | (f2bf(hi) << 16); }
; __device__ __forceinline__ void transpose_item(const float* W, int K, int N, bf16* WT, bool upmap, LAS float* scr, int item, int lane) {
;     ...
;     const int c = lane & 7;
; #pragma unroll
;     for (int j = 0; j < 4; ++j) { const int n = (lane >> 3) + 8 * j; const LAS float* s = scr + (8 * c) * 33 + n;
;         v4u o; o.x = pk2(s[0 * 33], s[1 * 33]); o.y = pk2(s[2 * 33], s[3 * 33]); o.z = pk2(s[4 * 33], s[5 * 33]); o.w = pk2(s[6 * 33], s[7 * 33]);
;         *(GAS v4u*)(WT + (size_t)(d0 + n) * K + k0 + 8 * c) = o; }
;     LDS_WAIT(); asm volatile("" ::: "memory");
	v_bfe_u32 v3, v30, 16, 1
	s_lshl_b64 s[4:5], s[4:5], 1
	v_add3_u32 v3, v30, v3, s33
	s_waitcnt lgkmcnt(0)
	v_bfe_u32 v8, v32, 16, 1
	s_add_u32 s4, s10, s4
	v_lshrrev_b32_e32 v3, 16, v3
	v_add3_u32 v8, v32, v8, s33
	v_or_b32_e32 v34, s2, v5
	s_addc_u32 s5, s9, s5
	v_lshlrev_b32_e32 v208, 1, v6
	v_and_or_b32 v17, v8, s80, v3
	v_ashrrev_i32_e32 v35, 31, v34
	v_bfe_u32 v3, v9, 16, 1
	v_lshl_add_u64 v[18:19], s[4:5], 0, v[208:209]
	v_lshlrev_b64 v[34:35], 11, v[34:35]
	v_add3_u32 v3, v9, v3, s33
	v_bfe_u32 v8, v21, 16, 1
	v_lshl_add_u64 v[34:35], v[18:19], 0, v[34:35]
	v_lshrrev_b32_e32 v3, 16, v3
	v_add3_u32 v8, v21, v8, s33
	global_store_dwordx4 v[34:35], v[14:17], off
	ds_read2_b32 v[20:21], v7 offset0:16 offset1:24
	v_or_b32_e32 v34, s2, v12
	v_and_or_b32 v14, v8, s80, v3
	v_bfe_u32 v3, v23, 16, 1
	v_add3_u32 v3, v23, v3, s33
	v_bfe_u32 v8, v25, 16, 1
	v_lshrrev_b32_e32 v3, 16, v3
	v_add3_u32 v8, v25, v8, s33
	v_and_or_b32 v15, v8, s80, v3
	v_bfe_u32 v3, v27, 16, 1
	v_add3_u32 v3, v27, v3, s33
	v_bfe_u32 v8, v29, 16, 1
	v_lshrrev_b32_e32 v3, 16, v3
	v_add3_u32 v8, v29, v8, s33
	v_and_or_b32 v16, v8, s80, v3
	v_bfe_u32 v3, v31, 16, 1
	v_add3_u32 v3, v31, v3, s33
	v_bfe_u32 v8, v33, 16, 1
	v_lshrrev_b32_e32 v3, 16, v3
	v_add3_u32 v8, v33, v8, s33
	v_and_or_b32 v17, v8, s80, v3
	v_or_b32_e32 v8, s2, v11
	v_ashrrev_i32_e32 v9, 31, v8
	v_lshlrev_b64 v[8:9], 11, v[8:9]
	v_lshl_add_u64 v[8:9], v[18:19], 0, v[8:9]
	global_store_dwordx4 v[8:9], v[14:17], off
	ds_read2_b32 v[8:9], v7 offset0:49 offset1:57
	ds_read2_b32 v[22:23], v7 offset0:82 offset1:90
	ds_read2_b32 v[24:25], v7 offset0:115 offset1:123
	s_waitcnt lgkmcnt(3)
	v_bfe_u32 v3, v20, 16, 1
	v_add3_u32 v3, v20, v3, s33
	s_waitcnt lgkmcnt(2)
	v_bfe_u32 v10, v8, 16, 1
	ds_read2_b32 v[26:27], v7 offset0:148 offset1:156
	v_lshrrev_b32_e32 v3, 16, v3
	v_add3_u32 v8, v8, v10, s33
	ds_read2_b32 v[28:29], v7 offset0:181 offset1:189
	v_and_or_b32 v14, v8, s80, v3
	s_waitcnt lgkmcnt(3)
	v_bfe_u32 v3, v22, 16, 1
	v_add3_u32 v3, v22, v3, s33
	s_waitcnt lgkmcnt(2)
	v_bfe_u32 v8, v24, 16, 1
	ds_read2_b32 v[30:31], v7 offset0:214 offset1:222
	v_lshrrev_b32_e32 v3, 16, v3
	v_add3_u32 v8, v24, v8, s33
	ds_read2_b32 v[32:33], v7 offset0:247 offset1:255
	v_and_or_b32 v15, v8, s80, v3
	s_waitcnt lgkmcnt(3)
	v_bfe_u32 v3, v26, 16, 1
	v_add3_u32 v3, v26, v3, s33
	s_waitcnt lgkmcnt(2)
	v_bfe_u32 v8, v28, 16, 1
	v_lshrrev_b32_e32 v3, 16, v3
	v_add3_u32 v8, v28, v8, s33
	v_and_or_b32 v16, v8, s80, v3
	s_waitcnt lgkmcnt(1)
	v_bfe_u32 v3, v30, 16, 1
	v_add3_u32 v3, v30, v3, s33
	s_waitcnt lgkmcnt(0)
	v_bfe_u32 v8, v32, 16, 1
	v_lshrrev_b32_e32 v3, 16, v3
	v_add3_u32 v8, v32, v8, s33
	v_and_or_b32 v17, v8, s80, v3
	v_ashrrev_i32_e32 v35, 31, v34
	v_bfe_u32 v3, v21, 16, 1
	v_lshlrev_b64 v[34:35], 11, v[34:35]
	v_add3_u32 v3, v21, v3, s33
	v_bfe_u32 v8, v9, 16, 1
	v_lshl_add_u64 v[34:35], v[18:19], 0, v[34:35]
	v_lshrrev_b32_e32 v3, 16, v3
	v_add3_u32 v8, v9, v8, s33
	global_store_dwordx4 v[34:35], v[14:17], off
	s_nop 1
	v_and_or_b32 v14, v8, s80, v3
	v_bfe_u32 v3, v23, 16, 1
	v_add3_u32 v3, v23, v3, s33
	v_bfe_u32 v8, v25, 16, 1
	v_lshrrev_b32_e32 v3, 16, v3
	v_add3_u32 v8, v25, v8, s33
	v_and_or_b32 v15, v8, s80, v3
	v_bfe_u32 v3, v27, 16, 1
	v_add3_u32 v3, v27, v3, s33
	v_bfe_u32 v8, v29, 16, 1
	v_lshrrev_b32_e32 v3, 16, v3
	v_add3_u32 v8, v29, v8, s33
	v_and_or_b32 v16, v8, s80, v3
	v_bfe_u32 v3, v31, 16, 1
	v_add3_u32 v3, v31, v3, s33
	v_bfe_u32 v8, v33, 16, 1
	v_lshrrev_b32_e32 v3, 16, v3
	v_add3_u32 v8, v33, v8, s33
	v_and_or_b32 v17, v8, s80, v3
	v_or_b32_e32 v8, s2, v13
	v_ashrrev_i32_e32 v9, 31, v8
	v_lshlrev_b64 v[8:9], 11, v[8:9]
	v_lshl_add_u64 v[8:9], v[18:19], 0, v[8:9]
	global_store_dwordx4 v[8:9], v[14:17], off
	s_waitcnt lgkmcnt(0)
	s_branch .LBB0_408
